# v25 + P7 rstd loads prefetched 3 row-groups ahead + P2 and P6 residual-input loads prefetched 3 row-groups ahead (counted vmcnt)
# baseline (speedup 1.0000x reference)
; __device__ __forceinline__ unsigned cvt_pk_bf16(float lo, float hi) { unsigned r; asm volatile("v_cvt_pk_bf16_f32 %0, %1, %2" : "=v"(r) : "v"(lo), "v"(hi)); return r; }
;     __device__ __forceinline__ void operator()(const f32x4 (&acc)[2][2][4][2], const Unit& u, int wr, int wc, int fr, int fq) const {
;         const int row0 = u.pm * BM + wr * 64 + fr, col0 = u.pn * BM + wc * 32 + 8 * fq;
;         f32x4 gv[2][2];
;         if constexpr (WX) {
; #pragma unroll
;             for (int bj = 0; bj < 2; ++bj)
; #pragma unroll
;                 for (int n = 0; n < 2; ++n) gv[bj][n] = *(const f32x4*)(gn + col0 + bj * HALF + 4 * n);
;         }
; #pragma unroll
;         for (int ai = 0; ai < 2; ++ai)
; #pragma unroll
;             for (int m = 0; m < 4; ++m) {
;                 const int row = row0 + ai * HALF + m * 16;
;                 const float* xr = (row < M_P) ? xin_p + (size_t)row * DM : xin_s + (size_t)(row - M_P) * DM;
;                 float* orow = out + (size_t)row * DM;
;                 float ss = 0.f;
; #pragma unroll
;                 for (int bj = 0; bj < 2; ++bj) {
;                     f32x4 o[2];
; #pragma unroll
;                     for (int n = 0; n < 2; ++n) { const f32x4 xv = *(const f32x4*)(xr + col0 + bj * HALF + 4 * n); o[n] = xv + acc[ai][bj][m][n] * (0.5f * ALPHA2); *(f32x4*)(orow + col0 + bj * HALF + 4 * n) = o[n]; }
;                     if constexpr (WX) {
; #pragma unroll
;                         for (int n = 0; n < 2; ++n) ss += (o[n][0] * o[n][0] + o[n][1] * o[n][1]) + (o[n][2] * o[n][2] + o[n][3] * o[n][3]);
;                         const f32x4 a = o[0] * gv[bj][0], b = o[1] * gv[bj][1];
;                         u32x4 w; w.x = cvt_pk_bf16(a[0], a[1]); w.y = cvt_pk_bf16(a[2], a[3]); w.z = cvt_pk_bf16(b[0], b[1]); w.w = cvt_pk_bf16(b[2], b[3]);
;                         *(u32x4*)(xn + (size_t)row * DM + col0 + bj * HALF) = w;
;                     }
;                 }
;                 if constexpr (WX) { ss += __shfl_xor(ss, 16); ss += __shfl_xor(ss, 32); if (fq == 0) ssq[((size_t)u.pn * MROWS + row) * 4 + wc] = ss; }
.LBB0_1042:
	v_lshl_or_b32 v162, s48, 8, v172
	v_ashrrev_i32_e32 v163, 31, v162
	v_lshl_add_u64 v[60:61], v[162:163], 2, s[46:47]
	global_load_dwordx4 v[68:71], v[60:61], off offset:16
	global_load_dwordx4 v[76:79], v[60:61], off
	global_load_dwordx4 v[56:59], v[60:61], off offset:528
	s_nop 0
	global_load_dwordx4 v[60:63], v[60:61], off offset:512
	v_lshl_add_u32 v164, s50, 8, v170
	v_cmp_lt_i32_e32 vcc, s67, v164
	s_and_saveexec_b64 s[16:17], vcc
	s_xor_b64 s[16:17], exec, s[16:17]
	v_add_u32_e32 v152, 0xffffc000, v164
	v_lshlrev_b64 v[166:167], 12, v[152:153]
	v_lshl_add_u64 v[168:169], s[10:11], 0, v[166:167]
	v_mov_b32_e32 v165, v153
	s_andn2_saveexec_b64 s[16:17], s[16:17]
	v_ashrrev_i32_e32 v165, 31, v164
	v_lshlrev_b64 v[166:167], 12, v[164:165]
	v_lshl_add_u64 v[168:169], s[22:23], 0, v[166:167]
	s_or_b64 exec, exec, s[16:17]
	v_lshlrev_b64 v[166:167], 2, v[162:163]
	v_lshl_add_u64 v[168:169], v[168:169], 0, v[166:167]
	v_mov_b32_e32 v250, v168
	v_mov_b32_e32 v251, v169
	v_mov_b32_e32 v254, 0x10000
	v_mov_b32_e32 v255, 0
	v_lshl_add_u64 v[252:253], v[254:255], 0, v[250:251]
	global_load_dwordx4 v[214:217], v[252:253], off
	global_load_dwordx4 v[218:221], v[252:253], off offset:16
	global_load_dwordx4 v[222:225], v[252:253], off offset:512
	global_load_dwordx4 v[226:229], v[252:253], off offset:528
	v_mov_b32_e32 v254, 0x20000
	v_mov_b32_e32 v255, 0
	v_lshl_add_u64 v[252:253], v[254:255], 0, v[250:251]
	global_load_dwordx4 v[230:233], v[252:253], off
	global_load_dwordx4 v[234:237], v[252:253], off offset:16
	global_load_dwordx4 v[242:245], v[252:253], off offset:512
	global_load_dwordx4 v[246:249], v[252:253], off offset:528
	v_mov_b32_e32 v254, 0x30000
	v_mov_b32_e32 v255, 0
	v_lshl_add_u64 v[252:253], v[254:255], 0, v[250:251]
	global_load_dwordx4 v[192:195], v[252:253], off
	global_load_dwordx4 v[196:199], v[252:253], off offset:16
	global_load_dwordx4 v[200:203], v[252:253], off offset:512
	global_load_dwordx4 v[204:207], v[252:253], off offset:528
	global_load_dwordx4 v[176:179], v[168:169], off
	v_lshlrev_b64 v[180:181], 12, v[164:165]
	v_lshl_add_u64 v[180:181], s[22:23], 0, v[180:181]
	v_lshl_add_u64 v[180:181], v[180:181], 0, v[166:167]
	v_lshlrev_b64 v[182:183], 11, v[164:165]
	v_lshl_add_u64 v[182:183], s[20:21], 0, v[182:183]
	v_lshl_add_u64 v[182:183], v[162:163], 1, v[182:183]
	s_mul_hi_i32 s49, s48, 0xc000
	s_mul_i32 s48, s48, 0xc000
	s_waitcnt vmcnt(0)
	v_pk_add_f32 v[142:143], v[142:143], v[178:179]
	v_pk_add_f32 v[140:141], v[140:141], v[176:177]
	global_store_dwordx4 v[180:181], v[140:143], off
	global_load_dwordx4 v[176:179], v[168:169], off offset:16
	v_pk_mul_f32 v[184:185], v[78:79], v[142:143]
	v_pk_mul_f32 v[186:187], v[76:77], v[140:141]
	v_mul_f32_e32 v141, v141, v141
	v_mul_f32_e32 v143, v143, v143
	v_fmac_f32_e32 v141, v140, v140
	v_fmac_f32_e32 v143, v142, v142
	v_add_f32_e32 v140, v141, v143
	s_waitcnt vmcnt(0)
	v_pk_add_f32 v[136:137], v[136:137], v[176:177]
	v_pk_add_f32 v[138:139], v[138:139], v[178:179]
	v_pk_mul_f32 v[178:179], v[68:69], v[136:137]
	global_store_dwordx4 v[180:181], v[136:139], off offset:16
	v_pk_mul_f32 v[188:189], v[70:71], v[138:139]
	v_cvt_pk_bf16_f32 v176, v186, v187
	v_cvt_pk_bf16_f32 v177, v184, v185
	v_cvt_pk_bf16_f32 v178, v178, v179
	s_nop 0
	v_cvt_pk_bf16_f32 v179, v188, v189
	global_store_dwordx4 v[182:183], v[176:179], off
	global_load_dwordx4 v[176:179], v[168:169], off offset:512
	v_mul_f32_e32 v137, v137, v137
	v_mul_f32_e32 v139, v139, v139
	v_fmac_f32_e32 v137, v136, v136
	v_fmac_f32_e32 v139, v138, v138
	v_add_f32_e32 v136, v137, v139
	v_add_f32_e32 v136, v140, v136
	s_waitcnt vmcnt(0)
	v_pk_add_f32 v[134:135], v[134:135], v[178:179]
	v_pk_add_f32 v[132:133], v[132:133], v[176:177]
	global_store_dwordx4 v[180:181], v[132:135], off offset:512
	global_load_dwordx4 v[176:179], v[168:169], off offset:528
	v_mul_f32_e32 v137, v133, v133
	v_mul_f32_e32 v138, v135, v135
	v_fmac_f32_e32 v137, v132, v132
	v_fmac_f32_e32 v138, v134, v134
	v_add_f32_e32 v137, v137, v138
	v_add_f32_e32 v136, v136, v137
	v_pk_mul_f32 v[132:133], v[60:61], v[132:133]
	v_pk_mul_f32 v[134:135], v[62:63], v[134:135]
	s_waitcnt vmcnt(0)
	v_pk_add_f32 v[130:131], v[130:131], v[178:179]
	v_pk_add_f32 v[128:129], v[128:129], v[176:177]
	v_mul_f32_e32 v138, v131, v131
	v_mul_f32_e32 v137, v129, v129
	v_fmac_f32_e32 v137, v128, v128
	v_fmac_f32_e32 v138, v130, v130
	v_add_f32_e32 v137, v137, v138
	v_add_f32_e32 v140, v136, v137
	ds_bpermute_b32 v141, v211, v140
	global_store_dwordx4 v[180:181], v[128:131], off offset:528
	v_pk_mul_f32 v[138:139], v[56:57], v[128:129]
	v_pk_mul_f32 v[136:137], v[58:59], v[130:131]
	v_cvt_pk_bf16_f32 v130, v132, v133
	s_waitcnt lgkmcnt(0)
	v_add_f32_e32 v128, v140, v141
	ds_bpermute_b32 v129, v212, v128
	v_cvt_pk_bf16_f32 v131, v134, v135
	v_cvt_pk_bf16_f32 v132, v138, v139
	v_cvt_pk_bf16_f32 v133, v136, v137
	global_store_dwordx4 v[182:183], v[130:133], off offset:256
	s_and_saveexec_b64 s[16:17], s[6:7]
	s_cbranch_execz .LBB0_1048
	v_lshl_add_u64 v[130:131], v[164:165], 0, s[48:49]
	v_lshl_add_u64 v[130:131], v[130:131], 4, s[36:37]
	s_waitcnt lgkmcnt(0)
	v_add_f32_e32 v128, v128, v129
	global_store_dword v[130:131], v128, off
; __device__ __forceinline__ unsigned cvt_pk_bf16(float lo, float hi) { unsigned r; asm volatile("v_cvt_pk_bf16_f32 %0, %1, %2" : "=v"(r) : "v"(lo), "v"(hi)); return r; }
;     __device__ __forceinline__ void operator()(const f32x4 (&acc)[2][2][4][2], const Unit& u, int wr, int wc, int fr, int fq) const {
;     ...
;                 const int row = row0 + ai * HALF + m * 16;
;                 const float* xr = (row < M_P) ? xin_p + (size_t)row * DM : xin_s + (size_t)(row - M_P) * DM;
;                 float* orow = out + (size_t)row * DM;
;                 float ss = 0.f;
; #pragma unroll
;                 for (int bj = 0; bj < 2; ++bj) {
;                     f32x4 o[2];
; #pragma unroll
;                     for (int n = 0; n < 2; ++n) { const f32x4 xv = *(const f32x4*)(xr + col0 + bj * HALF + 4 * n); o[n] = xv + acc[ai][bj][m][n] * (0.5f * ALPHA2); *(f32x4*)(orow + col0 + bj * HALF + 4 * n) = o[n]; }
;                     if constexpr (WX) {
; #pragma unroll
;                         for (int n = 0; n < 2; ++n) ss += (o[n][0] * o[n][0] + o[n][1] * o[n][1]) + (o[n][2] * o[n][2] + o[n][3] * o[n][3]);
;                         const f32x4 a = o[0] * gv[bj][0], b = o[1] * gv[bj][1];
;                         u32x4 w; w.x = cvt_pk_bf16(a[0], a[1]); w.y = cvt_pk_bf16(a[2], a[3]); w.z = cvt_pk_bf16(b[0], b[1]); w.w = cvt_pk_bf16(b[2], b[3]);
;                         *(u32x4*)(xn + (size_t)row * DM + col0 + bj * HALF) = w;
;                     }
;                 }
;                 if constexpr (WX) { ss += __shfl_xor(ss, 16); ss += __shfl_xor(ss, 32); if (fq == 0) ssq[((size_t)u.pn * MROWS + row) * 4 + wc] = ss; }
.LBB0_1048:
	s_or_b64 exec, exec, s[16:17]
	s_waitcnt lgkmcnt(0)
	v_or_b32_e32 v128, 16, v164
	v_cmp_lt_i32_e32 vcc, s67, v128
	s_and_saveexec_b64 s[16:17], vcc
	s_xor_b64 s[16:17], exec, s[16:17]
	v_add_u32_e32 v152, 0xffffc010, v164
	v_lshlrev_b64 v[130:131], 12, v[152:153]
	v_lshl_add_u64 v[130:131], s[10:11], 0, v[130:131]
	v_mov_b32_e32 v129, v153
	s_andn2_saveexec_b64 s[16:17], s[16:17]
	v_ashrrev_i32_e32 v129, 31, v128
	v_lshlrev_b64 v[130:131], 12, v[128:129]
	v_lshl_add_u64 v[130:131], s[22:23], 0, v[130:131]
	s_or_b64 exec, exec, s[16:17]
	v_lshl_add_u64 v[134:135], v[130:131], 0, v[166:167]
	v_mov_b32_e32 v254, 0x80000
	v_mov_b32_e32 v255, 0
	v_lshl_add_u64 v[252:253], v[254:255], 0, v[250:251]
	v_lshlrev_b64 v[136:137], 12, v[128:129]
	v_lshl_add_u64 v[136:137], s[22:23], 0, v[136:137]
	v_lshl_add_u64 v[136:137], v[136:137], 0, v[166:167]
	v_lshlrev_b64 v[138:139], 11, v[128:129]
	v_lshl_add_u64 v[138:139], s[20:21], 0, v[138:139]
	v_lshl_add_u64 v[138:139], v[162:163], 1, v[138:139]
	s_waitcnt vmcnt(21)
	v_pk_add_f32 v[126:127], v[126:127], v[216:217]
	v_pk_add_f32 v[124:125], v[124:125], v[214:215]
	global_load_dwordx4 v[214:217], v[252:253], off
	global_store_dwordx4 v[136:137], v[124:127], off
	s_nop 0
	v_pk_mul_f32 v[140:141], v[78:79], v[126:127]
	v_pk_mul_f32 v[142:143], v[76:77], v[124:125]
	v_mul_f32_e32 v125, v125, v125
	v_mul_f32_e32 v127, v127, v127
	v_fmac_f32_e32 v125, v124, v124
	v_fmac_f32_e32 v127, v126, v126
	v_add_f32_e32 v124, v125, v127
	s_waitcnt vmcnt(22)
	v_pk_add_f32 v[120:121], v[120:121], v[218:219]
	v_pk_add_f32 v[122:123], v[122:123], v[220:221]
	global_load_dwordx4 v[218:221], v[252:253], off offset:16
	v_pk_mul_f32 v[132:133], v[68:69], v[120:121]
	global_store_dwordx4 v[136:137], v[120:123], off offset:16
	v_pk_mul_f32 v[168:169], v[70:71], v[122:123]
	v_cvt_pk_bf16_f32 v130, v142, v143
	v_cvt_pk_bf16_f32 v131, v140, v141
	v_cvt_pk_bf16_f32 v132, v132, v133
	s_nop 0
	v_cvt_pk_bf16_f32 v133, v168, v169
	global_store_dwordx4 v[138:139], v[130:133], off
	s_nop 0
	v_mul_f32_e32 v121, v121, v121
	v_mul_f32_e32 v123, v123, v123
	v_fmac_f32_e32 v121, v120, v120
	v_fmac_f32_e32 v123, v122, v122
	v_add_f32_e32 v120, v121, v123
	v_add_f32_e32 v120, v124, v120
	s_waitcnt vmcnt(24)
	v_pk_add_f32 v[118:119], v[118:119], v[224:225]
	v_pk_add_f32 v[116:117], v[116:117], v[222:223]
	global_load_dwordx4 v[222:225], v[252:253], off offset:512
	global_store_dwordx4 v[136:137], v[116:119], off offset:512
	s_nop 0
	v_mul_f32_e32 v121, v117, v117
	v_mul_f32_e32 v122, v119, v119
	v_fmac_f32_e32 v121, v116, v116
	v_fmac_f32_e32 v122, v118, v118
	v_add_f32_e32 v121, v121, v122
	v_add_f32_e32 v120, v120, v121
	v_pk_mul_f32 v[116:117], v[60:61], v[116:117]
	v_pk_mul_f32 v[118:119], v[62:63], v[118:119]
	s_waitcnt vmcnt(25)
	v_pk_add_f32 v[114:115], v[114:115], v[228:229]
	v_pk_add_f32 v[112:113], v[112:113], v[226:227]
	global_load_dwordx4 v[226:229], v[252:253], off offset:528
	v_mul_f32_e32 v122, v115, v115
	v_mul_f32_e32 v121, v113, v113
	v_fmac_f32_e32 v121, v112, v112
	v_fmac_f32_e32 v122, v114, v114
	v_add_f32_e32 v121, v121, v122
	v_add_f32_e32 v124, v120, v121
	ds_bpermute_b32 v125, v211, v124
	global_store_dwordx4 v[136:137], v[112:115], off offset:528
	v_pk_mul_f32 v[122:123], v[56:57], v[112:113]
	v_pk_mul_f32 v[120:121], v[58:59], v[114:115]
	v_cvt_pk_bf16_f32 v114, v116, v117
	s_waitcnt lgkmcnt(0)
	v_add_f32_e32 v112, v124, v125
	ds_bpermute_b32 v113, v212, v112
	v_cvt_pk_bf16_f32 v115, v118, v119
	v_cvt_pk_bf16_f32 v116, v122, v123
	v_cvt_pk_bf16_f32 v117, v120, v121
	global_store_dwordx4 v[138:139], v[114:117], off offset:256
	s_and_saveexec_b64 s[16:17], s[6:7]
	s_cbranch_execz .LBB0_1054
	v_lshl_add_u64 v[114:115], v[128:129], 0, s[48:49]
	v_lshl_add_u64 v[114:115], v[114:115], 4, s[36:37]
	s_waitcnt lgkmcnt(0)
	v_add_f32_e32 v112, v112, v113
	global_store_dword v[114:115], v112, off
.LBB0_1054:
	s_or_b64 exec, exec, s[16:17]
	s_waitcnt lgkmcnt(0)
	v_or_b32_e32 v112, 32, v164
	v_cmp_lt_i32_e32 vcc, s67, v112
	s_and_saveexec_b64 s[16:17], vcc
	s_xor_b64 s[16:17], exec, s[16:17]
	v_add_u32_e32 v152, 0xffffc020, v164
	v_lshlrev_b64 v[114:115], 12, v[152:153]
	v_lshl_add_u64 v[114:115], s[10:11], 0, v[114:115]
	v_mov_b32_e32 v113, v153
	s_andn2_saveexec_b64 s[16:17], s[16:17]
	v_ashrrev_i32_e32 v113, 31, v112
	v_lshlrev_b64 v[114:115], 12, v[112:113]
	v_lshl_add_u64 v[114:115], s[22:23], 0, v[114:115]
	s_or_b64 exec, exec, s[16:17]
	v_lshl_add_u64 v[118:119], v[114:115], 0, v[166:167]
	v_mov_b32_e32 v254, 0x90000
	v_mov_b32_e32 v255, 0
	v_lshl_add_u64 v[252:253], v[254:255], 0, v[250:251]
	v_lshlrev_b64 v[120:121], 12, v[112:113]
	v_lshl_add_u64 v[120:121], s[22:23], 0, v[120:121]
	v_lshl_add_u64 v[120:121], v[120:121], 0, v[166:167]
	v_lshlrev_b64 v[122:123], 11, v[112:113]
	v_lshl_add_u64 v[122:123], s[20:21], 0, v[122:123]
	v_lshl_add_u64 v[122:123], v[162:163], 1, v[122:123]
	s_waitcnt vmcnt(27)
	v_pk_add_f32 v[110:111], v[110:111], v[232:233]
	v_pk_add_f32 v[108:109], v[108:109], v[230:231]
	global_load_dwordx4 v[230:233], v[252:253], off
	global_store_dwordx4 v[120:121], v[108:111], off
	s_nop 0
	v_pk_mul_f32 v[124:125], v[78:79], v[110:111]
	v_pk_mul_f32 v[126:127], v[76:77], v[108:109]
	v_mul_f32_e32 v109, v109, v109
	v_mul_f32_e32 v111, v111, v111
	v_fmac_f32_e32 v109, v108, v108
	v_fmac_f32_e32 v111, v110, v110
	v_add_f32_e32 v108, v109, v111
	s_waitcnt vmcnt(28)
; __device__ __forceinline__ unsigned cvt_pk_bf16(float lo, float hi) { unsigned r; asm volatile("v_cvt_pk_bf16_f32 %0, %1, %2" : "=v"(r) : "v"(lo), "v"(hi)); return r; }
;     __device__ __forceinline__ void operator()(const f32x4 (&acc)[2][2][4][2], const Unit& u, int wr, int wc, int fr, int fq) const {
;     ...
;                 const int row = row0 + ai * HALF + m * 16;
;                 const float* xr = (row < M_P) ? xin_p + (size_t)row * DM : xin_s + (size_t)(row - M_P) * DM;
;                 float* orow = out + (size_t)row * DM;
;                 float ss = 0.f;
; #pragma unroll
;                 for (int bj = 0; bj < 2; ++bj) {
;                     f32x4 o[2];
; #pragma unroll
;                     for (int n = 0; n < 2; ++n) { const f32x4 xv = *(const f32x4*)(xr + col0 + bj * HALF + 4 * n); o[n] = xv + acc[ai][bj][m][n] * (0.5f * ALPHA2); *(f32x4*)(orow + col0 + bj * HALF + 4 * n) = o[n]; }
;                     if constexpr (WX) {
; #pragma unroll
;                         for (int n = 0; n < 2; ++n) ss += (o[n][0] * o[n][0] + o[n][1] * o[n][1]) + (o[n][2] * o[n][2] + o[n][3] * o[n][3]);
;                         const f32x4 a = o[0] * gv[bj][0], b = o[1] * gv[bj][1];
;                         u32x4 w; w.x = cvt_pk_bf16(a[0], a[1]); w.y = cvt_pk_bf16(a[2], a[3]); w.z = cvt_pk_bf16(b[0], b[1]); w.w = cvt_pk_bf16(b[2], b[3]);
;                         *(u32x4*)(xn + (size_t)row * DM + col0 + bj * HALF) = w;
;                     }
;                 }
;                 if constexpr (WX) { ss += __shfl_xor(ss, 16); ss += __shfl_xor(ss, 32); if (fq == 0) ssq[((size_t)u.pn * MROWS + row) * 4 + wc] = ss; }
	v_pk_add_f32 v[104:105], v[104:105], v[234:235]
	v_pk_add_f32 v[106:107], v[106:107], v[236:237]
	global_load_dwordx4 v[234:237], v[252:253], off offset:16
	v_pk_mul_f32 v[116:117], v[68:69], v[104:105]
	global_store_dwordx4 v[120:121], v[104:107], off offset:16
	v_pk_mul_f32 v[128:129], v[70:71], v[106:107]
	v_cvt_pk_bf16_f32 v114, v126, v127
	v_cvt_pk_bf16_f32 v115, v124, v125
	v_cvt_pk_bf16_f32 v116, v116, v117
	s_nop 0
	v_cvt_pk_bf16_f32 v117, v128, v129
	global_store_dwordx4 v[122:123], v[114:117], off
	s_nop 0
	v_mul_f32_e32 v105, v105, v105
	v_mul_f32_e32 v107, v107, v107
	v_fmac_f32_e32 v105, v104, v104
	v_fmac_f32_e32 v107, v106, v106
	v_add_f32_e32 v104, v105, v107
	v_add_f32_e32 v104, v108, v104
	s_waitcnt vmcnt(30)
	v_pk_add_f32 v[102:103], v[102:103], v[244:245]
	v_pk_add_f32 v[100:101], v[100:101], v[242:243]
	global_load_dwordx4 v[242:245], v[252:253], off offset:512
	global_store_dwordx4 v[120:121], v[100:103], off offset:512
	s_nop 0
	v_mul_f32_e32 v105, v101, v101
	v_mul_f32_e32 v106, v103, v103
	v_fmac_f32_e32 v105, v100, v100
	v_fmac_f32_e32 v106, v102, v102
	v_add_f32_e32 v105, v105, v106
	v_add_f32_e32 v104, v104, v105
	v_pk_mul_f32 v[100:101], v[60:61], v[100:101]
	v_pk_mul_f32 v[102:103], v[62:63], v[102:103]
	s_waitcnt vmcnt(31)
	v_pk_add_f32 v[98:99], v[98:99], v[248:249]
	v_pk_add_f32 v[96:97], v[96:97], v[246:247]
	global_load_dwordx4 v[246:249], v[252:253], off offset:528
	v_mul_f32_e32 v106, v99, v99
	v_mul_f32_e32 v105, v97, v97
	v_fmac_f32_e32 v105, v96, v96
	v_fmac_f32_e32 v106, v98, v98
	v_add_f32_e32 v105, v105, v106
	v_add_f32_e32 v108, v104, v105
	ds_bpermute_b32 v109, v211, v108
	global_store_dwordx4 v[120:121], v[96:99], off offset:528
	v_pk_mul_f32 v[106:107], v[56:57], v[96:97]
	v_pk_mul_f32 v[104:105], v[58:59], v[98:99]
	v_cvt_pk_bf16_f32 v98, v100, v101
	s_waitcnt lgkmcnt(0)
	v_add_f32_e32 v96, v108, v109
	ds_bpermute_b32 v97, v212, v96
	v_cvt_pk_bf16_f32 v99, v102, v103
	v_cvt_pk_bf16_f32 v100, v106, v107
	v_cvt_pk_bf16_f32 v101, v104, v105
	global_store_dwordx4 v[122:123], v[98:101], off offset:256
	s_and_saveexec_b64 s[16:17], s[6:7]
	s_cbranch_execz .LBB0_1060
	v_lshl_add_u64 v[98:99], v[112:113], 0, s[48:49]
	v_lshl_add_u64 v[98:99], v[98:99], 4, s[36:37]
	s_waitcnt lgkmcnt(0)
	v_add_f32_e32 v96, v96, v97
	global_store_dword v[98:99], v96, off
.LBB0_1060:
	s_or_b64 exec, exec, s[16:17]
	s_waitcnt lgkmcnt(0)
	v_or_b32_e32 v96, 48, v164
	v_cmp_lt_i32_e32 vcc, s67, v96
	s_and_saveexec_b64 s[16:17], vcc
	s_xor_b64 s[16:17], exec, s[16:17]
	v_add_u32_e32 v152, 0xffffc030, v164
	v_lshlrev_b64 v[98:99], 12, v[152:153]
	v_lshl_add_u64 v[98:99], s[10:11], 0, v[98:99]
	v_mov_b32_e32 v97, v153
	s_andn2_saveexec_b64 s[16:17], s[16:17]
	v_ashrrev_i32_e32 v97, 31, v96
	v_lshlrev_b64 v[98:99], 12, v[96:97]
	v_lshl_add_u64 v[98:99], s[22:23], 0, v[98:99]
	s_or_b64 exec, exec, s[16:17]
	v_lshl_add_u64 v[102:103], v[98:99], 0, v[166:167]
	v_mov_b32_e32 v254, 0xa0000
	v_mov_b32_e32 v255, 0
	v_lshl_add_u64 v[252:253], v[254:255], 0, v[250:251]
	v_lshlrev_b64 v[104:105], 12, v[96:97]
	v_lshl_add_u64 v[104:105], s[22:23], 0, v[104:105]
	v_lshl_add_u64 v[104:105], v[104:105], 0, v[166:167]
	v_lshlrev_b64 v[106:107], 11, v[96:97]
	v_lshl_add_u64 v[106:107], s[20:21], 0, v[106:107]
	v_lshl_add_u64 v[106:107], v[162:163], 1, v[106:107]
	s_waitcnt vmcnt(33)
	v_pk_add_f32 v[94:95], v[94:95], v[194:195]
	v_pk_add_f32 v[92:93], v[92:93], v[192:193]
	global_load_dwordx4 v[192:195], v[252:253], off
	global_store_dwordx4 v[104:105], v[92:95], off
	s_nop 0
	v_pk_mul_f32 v[108:109], v[78:79], v[94:95]
	v_pk_mul_f32 v[110:111], v[76:77], v[92:93]
	v_mul_f32_e32 v93, v93, v93
	v_mul_f32_e32 v95, v95, v95
	v_fmac_f32_e32 v93, v92, v92
	v_fmac_f32_e32 v95, v94, v94
	v_add_f32_e32 v92, v93, v95
	s_waitcnt vmcnt(34)
	v_pk_add_f32 v[88:89], v[88:89], v[196:197]
	v_pk_add_f32 v[90:91], v[90:91], v[198:199]
	global_load_dwordx4 v[196:199], v[252:253], off offset:16
	v_pk_mul_f32 v[100:101], v[68:69], v[88:89]
	global_store_dwordx4 v[104:105], v[88:91], off offset:16
	v_pk_mul_f32 v[112:113], v[70:71], v[90:91]
	v_cvt_pk_bf16_f32 v98, v110, v111
	v_cvt_pk_bf16_f32 v99, v108, v109
	v_cvt_pk_bf16_f32 v100, v100, v101
	s_nop 0
	v_cvt_pk_bf16_f32 v101, v112, v113
	global_store_dwordx4 v[106:107], v[98:101], off
	s_nop 0
	v_mul_f32_e32 v89, v89, v89
	v_mul_f32_e32 v91, v91, v91
	v_fmac_f32_e32 v89, v88, v88
	v_fmac_f32_e32 v91, v90, v90
	v_add_f32_e32 v88, v89, v91
	v_add_f32_e32 v88, v92, v88
	s_waitcnt vmcnt(36)
	v_pk_add_f32 v[86:87], v[86:87], v[202:203]
	v_pk_add_f32 v[84:85], v[84:85], v[200:201]
	global_load_dwordx4 v[200:203], v[252:253], off offset:512
	global_store_dwordx4 v[104:105], v[84:87], off offset:512
	s_nop 0
	v_mul_f32_e32 v89, v85, v85
	v_mul_f32_e32 v90, v87, v87
	v_fmac_f32_e32 v89, v84, v84
	v_fmac_f32_e32 v90, v86, v86
	v_add_f32_e32 v89, v89, v90
	v_add_f32_e32 v88, v88, v89
	v_pk_mul_f32 v[84:85], v[60:61], v[84:85]
	v_pk_mul_f32 v[86:87], v[62:63], v[86:87]
	s_waitcnt vmcnt(37)
	v_pk_add_f32 v[82:83], v[82:83], v[206:207]
	v_pk_add_f32 v[80:81], v[80:81], v[204:205]
	global_load_dwordx4 v[204:207], v[252:253], off offset:528
	v_mul_f32_e32 v90, v83, v83
	v_mul_f32_e32 v89, v81, v81
	v_fmac_f32_e32 v89, v80, v80
	v_fmac_f32_e32 v90, v82, v82
	v_add_f32_e32 v89, v89, v90
	v_add_f32_e32 v92, v88, v89
	ds_bpermute_b32 v93, v211, v92
	global_store_dwordx4 v[104:105], v[80:83], off offset:528
	v_pk_mul_f32 v[90:91], v[56:57], v[80:81]
	v_pk_mul_f32 v[88:89], v[58:59], v[82:83]
	v_cvt_pk_bf16_f32 v82, v84, v85
	s_waitcnt lgkmcnt(0)
	v_add_f32_e32 v80, v92, v93
	ds_bpermute_b32 v81, v212, v80
	v_cvt_pk_bf16_f32 v83, v86, v87
	v_cvt_pk_bf16_f32 v84, v90, v91
	v_cvt_pk_bf16_f32 v85, v88, v89
	global_store_dwordx4 v[106:107], v[82:85], off offset:256
	s_and_saveexec_b64 s[16:17], s[6:7]
	s_cbranch_execz .LBB0_1066
	v_lshl_add_u64 v[82:83], v[96:97], 0, s[48:49]
	v_lshl_add_u64 v[82:83], v[82:83], 4, s[36:37]
	s_waitcnt lgkmcnt(0)
	v_add_f32_e32 v80, v80, v81
	global_store_dword v[82:83], v80, off
; __device__ __forceinline__ unsigned cvt_pk_bf16(float lo, float hi) { unsigned r; asm volatile("v_cvt_pk_bf16_f32 %0, %1, %2" : "=v"(r) : "v"(lo), "v"(hi)); return r; }
;     __device__ __forceinline__ void operator()(const f32x4 (&acc)[2][2][4][2], const Unit& u, int wr, int wc, int fr, int fq) const {
;     ...
;                 const int row = row0 + ai * HALF + m * 16;
;                 const float* xr = (row < M_P) ? xin_p + (size_t)row * DM : xin_s + (size_t)(row - M_P) * DM;
;                 float* orow = out + (size_t)row * DM;
;                 float ss = 0.f;
; #pragma unroll
;                 for (int bj = 0; bj < 2; ++bj) {
;                     f32x4 o[2];
; #pragma unroll
;                     for (int n = 0; n < 2; ++n) { const f32x4 xv = *(const f32x4*)(xr + col0 + bj * HALF + 4 * n); o[n] = xv + acc[ai][bj][m][n] * (0.5f * ALPHA2); *(f32x4*)(orow + col0 + bj * HALF + 4 * n) = o[n]; }
;                     if constexpr (WX) {
; #pragma unroll
;                         for (int n = 0; n < 2; ++n) ss += (o[n][0] * o[n][0] + o[n][1] * o[n][1]) + (o[n][2] * o[n][2] + o[n][3] * o[n][3]);
;                         const f32x4 a = o[0] * gv[bj][0], b = o[1] * gv[bj][1];
;                         u32x4 w; w.x = cvt_pk_bf16(a[0], a[1]); w.y = cvt_pk_bf16(a[2], a[3]); w.z = cvt_pk_bf16(b[0], b[1]); w.w = cvt_pk_bf16(b[2], b[3]);
;                         *(u32x4*)(xn + (size_t)row * DM + col0 + bj * HALF) = w;
;                     }
;                 }
;                 if constexpr (WX) { ss += __shfl_xor(ss, 16); ss += __shfl_xor(ss, 32); if (fq == 0) ssq[((size_t)u.pn * MROWS + row) * 4 + wc] = ss; }
.LBB0_1066:
	s_or_b64 exec, exec, s[16:17]
	s_waitcnt lgkmcnt(0)
	v_add_u32_e32 v80, 0x80, v164
	v_cmp_lt_i32_e32 vcc, s68, v164
	s_and_saveexec_b64 s[16:17], vcc
	s_xor_b64 s[16:17], exec, s[16:17]
	v_add_u32_e32 v152, 0xffffc080, v164
	v_lshlrev_b64 v[82:83], 12, v[152:153]
	v_lshl_add_u64 v[82:83], s[10:11], 0, v[82:83]
	v_mov_b32_e32 v81, v153
	s_andn2_saveexec_b64 s[16:17], s[16:17]
	v_ashrrev_i32_e32 v81, 31, v80
	v_lshlrev_b64 v[82:83], 12, v[80:81]
	v_lshl_add_u64 v[82:83], s[22:23], 0, v[82:83]
	s_or_b64 exec, exec, s[16:17]
	v_lshl_add_u64 v[86:87], v[82:83], 0, v[166:167]
	v_mov_b32_e32 v254, 0xb0000
	v_mov_b32_e32 v255, 0
	v_lshl_add_u64 v[252:253], v[254:255], 0, v[250:251]
	v_lshlrev_b64 v[88:89], 12, v[80:81]
	v_lshl_add_u64 v[88:89], s[22:23], 0, v[88:89]
	v_lshl_add_u64 v[88:89], v[88:89], 0, v[166:167]
	v_lshlrev_b64 v[90:91], 11, v[80:81]
	v_lshl_add_u64 v[90:91], s[20:21], 0, v[90:91]
	v_lshl_add_u64 v[90:91], v[162:163], 1, v[90:91]
	s_waitcnt vmcnt(29)
	v_pk_add_f32 v[74:75], v[74:75], v[216:217]
	v_pk_add_f32 v[72:73], v[72:73], v[214:215]
	global_load_dwordx4 v[214:217], v[252:253], off
	global_store_dwordx4 v[88:89], v[72:75], off
	s_nop 0
	v_pk_mul_f32 v[92:93], v[78:79], v[74:75]
	v_pk_mul_f32 v[94:95], v[76:77], v[72:73]
	v_mul_f32_e32 v73, v73, v73
	v_mul_f32_e32 v75, v75, v75
	v_fmac_f32_e32 v73, v72, v72
	v_fmac_f32_e32 v75, v74, v74
	v_add_f32_e32 v72, v73, v75
	s_waitcnt vmcnt(29)
	v_pk_add_f32 v[64:65], v[64:65], v[218:219]
	v_pk_add_f32 v[66:67], v[66:67], v[220:221]
	global_load_dwordx4 v[218:221], v[252:253], off offset:16
	v_pk_mul_f32 v[84:85], v[68:69], v[64:65]
	global_store_dwordx4 v[88:89], v[64:67], off offset:16
	v_pk_mul_f32 v[96:97], v[70:71], v[66:67]
	v_cvt_pk_bf16_f32 v82, v94, v95
	v_cvt_pk_bf16_f32 v83, v92, v93
	v_cvt_pk_bf16_f32 v84, v84, v85
	s_nop 0
	v_cvt_pk_bf16_f32 v85, v96, v97
	global_store_dwordx4 v[90:91], v[82:85], off
	s_nop 0
	v_mul_f32_e32 v65, v65, v65
	v_mul_f32_e32 v67, v67, v67
	v_fmac_f32_e32 v65, v64, v64
	v_fmac_f32_e32 v67, v66, v66
	v_add_f32_e32 v64, v65, v67
	v_add_f32_e32 v64, v72, v64
	s_waitcnt vmcnt(29)
	v_pk_add_f32 v[54:55], v[54:55], v[224:225]
	v_pk_add_f32 v[52:53], v[52:53], v[222:223]
	global_load_dwordx4 v[222:225], v[252:253], off offset:512
	global_store_dwordx4 v[88:89], v[52:55], off offset:512
	s_nop 0
	v_mul_f32_e32 v65, v53, v53
	v_mul_f32_e32 v66, v55, v55
	v_fmac_f32_e32 v65, v52, v52
	v_fmac_f32_e32 v66, v54, v54
	v_add_f32_e32 v65, v65, v66
	v_add_f32_e32 v64, v64, v65
	v_pk_mul_f32 v[52:53], v[60:61], v[52:53]
	v_pk_mul_f32 v[54:55], v[62:63], v[54:55]
	s_waitcnt vmcnt(29)
	v_pk_add_f32 v[50:51], v[50:51], v[228:229]
	v_pk_add_f32 v[48:49], v[48:49], v[226:227]
	global_load_dwordx4 v[226:229], v[252:253], off offset:528
	v_mul_f32_e32 v66, v51, v51
	v_mul_f32_e32 v65, v49, v49
	v_fmac_f32_e32 v65, v48, v48
	v_fmac_f32_e32 v66, v50, v50
	v_add_f32_e32 v65, v65, v66
	v_add_f32_e32 v72, v64, v65
	ds_bpermute_b32 v73, v211, v72
	global_store_dwordx4 v[88:89], v[48:51], off offset:528
	v_pk_mul_f32 v[66:67], v[56:57], v[48:49]
	v_pk_mul_f32 v[64:65], v[58:59], v[50:51]
	v_cvt_pk_bf16_f32 v50, v52, v53
	s_waitcnt lgkmcnt(0)
	v_add_f32_e32 v48, v72, v73
	ds_bpermute_b32 v49, v212, v48
	v_cvt_pk_bf16_f32 v51, v54, v55
	v_cvt_pk_bf16_f32 v52, v66, v67
	v_cvt_pk_bf16_f32 v53, v64, v65
	global_store_dwordx4 v[90:91], v[50:53], off offset:256
	s_and_saveexec_b64 s[16:17], s[6:7]
	s_cbranch_execz .LBB0_1072
	v_lshl_add_u64 v[50:51], v[80:81], 0, s[48:49]
	v_lshl_add_u64 v[50:51], v[50:51], 4, s[36:37]
	s_waitcnt lgkmcnt(0)
	v_add_f32_e32 v48, v48, v49
	global_store_dword v[50:51], v48, off
.LBB0_1072:
	s_or_b64 exec, exec, s[16:17]
	s_waitcnt lgkmcnt(0)
	v_add_u32_e32 v48, 0x90, v164
	v_cmp_lt_i32_e32 vcc, s69, v164
	s_and_saveexec_b64 s[16:17], vcc
	s_xor_b64 s[16:17], exec, s[16:17]
	v_add_u32_e32 v152, 0xffffc090, v164
	v_lshlrev_b64 v[50:51], 12, v[152:153]
	v_lshl_add_u64 v[50:51], s[10:11], 0, v[50:51]
	v_mov_b32_e32 v49, v153
	s_andn2_saveexec_b64 s[16:17], s[16:17]
	v_ashrrev_i32_e32 v49, 31, v48
	v_lshlrev_b64 v[50:51], 12, v[48:49]
	v_lshl_add_u64 v[50:51], s[22:23], 0, v[50:51]
	s_or_b64 exec, exec, s[16:17]
	v_lshl_add_u64 v[54:55], v[50:51], 0, v[166:167]
	s_nop 0
	v_lshlrev_b64 v[64:65], 12, v[48:49]
	v_lshl_add_u64 v[64:65], s[22:23], 0, v[64:65]
	v_lshl_add_u64 v[64:65], v[64:65], 0, v[166:167]
	v_lshlrev_b64 v[66:67], 11, v[48:49]
	v_lshl_add_u64 v[66:67], s[20:21], 0, v[66:67]
	v_lshl_add_u64 v[66:67], v[162:163], 1, v[66:67]
	s_waitcnt vmcnt(29)
	v_pk_add_f32 v[46:47], v[46:47], v[232:233]
	v_pk_add_f32 v[44:45], v[44:45], v[230:231]
	global_store_dwordx4 v[64:65], v[44:47], off
	s_nop 0
	v_pk_mul_f32 v[72:73], v[78:79], v[46:47]
	v_pk_mul_f32 v[74:75], v[76:77], v[44:45]
	v_mul_f32_e32 v45, v45, v45
	v_mul_f32_e32 v47, v47, v47
	v_fmac_f32_e32 v45, v44, v44
	v_fmac_f32_e32 v47, v46, v46
	v_add_f32_e32 v44, v45, v47
	s_waitcnt vmcnt(28)
	v_pk_add_f32 v[40:41], v[40:41], v[234:235]
	v_pk_add_f32 v[42:43], v[42:43], v[236:237]
	v_pk_mul_f32 v[52:53], v[68:69], v[40:41]
	global_store_dwordx4 v[64:65], v[40:43], off offset:16
	v_pk_mul_f32 v[80:81], v[70:71], v[42:43]
	v_cvt_pk_bf16_f32 v50, v74, v75
	v_cvt_pk_bf16_f32 v51, v72, v73
	v_cvt_pk_bf16_f32 v52, v52, v53
	s_nop 0
	v_cvt_pk_bf16_f32 v53, v80, v81
	global_store_dwordx4 v[66:67], v[50:53], off
	s_nop 0
	v_mul_f32_e32 v41, v41, v41
	v_mul_f32_e32 v43, v43, v43
	v_fmac_f32_e32 v41, v40, v40
	v_fmac_f32_e32 v43, v42, v42
	v_add_f32_e32 v40, v41, v43
	v_add_f32_e32 v40, v44, v40
	s_waitcnt vmcnt(27)
	v_pk_add_f32 v[38:39], v[38:39], v[244:245]
	v_pk_add_f32 v[36:37], v[36:37], v[242:243]
	global_store_dwordx4 v[64:65], v[36:39], off offset:512
	s_nop 0
	v_mul_f32_e32 v41, v37, v37
	v_mul_f32_e32 v42, v39, v39
	v_fmac_f32_e32 v41, v36, v36
	v_fmac_f32_e32 v42, v38, v38
	v_add_f32_e32 v41, v41, v42
	v_add_f32_e32 v40, v40, v41
	v_pk_mul_f32 v[36:37], v[60:61], v[36:37]
	v_pk_mul_f32 v[38:39], v[62:63], v[38:39]
	s_waitcnt vmcnt(26)
	v_pk_add_f32 v[34:35], v[34:35], v[248:249]
	v_pk_add_f32 v[32:33], v[32:33], v[246:247]
	v_mul_f32_e32 v42, v35, v35
	v_mul_f32_e32 v41, v33, v33
	v_fmac_f32_e32 v41, v32, v32
	v_fmac_f32_e32 v42, v34, v34
	v_add_f32_e32 v41, v41, v42
	v_add_f32_e32 v44, v40, v41
	ds_bpermute_b32 v45, v211, v44
	global_store_dwordx4 v[64:65], v[32:35], off offset:528
	v_pk_mul_f32 v[42:43], v[56:57], v[32:33]
	v_pk_mul_f32 v[40:41], v[58:59], v[34:35]
	v_cvt_pk_bf16_f32 v34, v36, v37
	s_waitcnt lgkmcnt(0)
	v_add_f32_e32 v32, v44, v45
	ds_bpermute_b32 v33, v212, v32
	v_cvt_pk_bf16_f32 v35, v38, v39
	v_cvt_pk_bf16_f32 v36, v42, v43
	v_cvt_pk_bf16_f32 v37, v40, v41
	global_store_dwordx4 v[66:67], v[34:37], off offset:256
	s_and_saveexec_b64 s[16:17], s[6:7]
	s_cbranch_execz .LBB0_1078
	v_lshl_add_u64 v[34:35], v[48:49], 0, s[48:49]
	v_lshl_add_u64 v[34:35], v[34:35], 4, s[36:37]
	s_waitcnt lgkmcnt(0)
	v_add_f32_e32 v32, v32, v33
	global_store_dword v[34:35], v32, off
; __device__ __forceinline__ unsigned cvt_pk_bf16(float lo, float hi) { unsigned r; asm volatile("v_cvt_pk_bf16_f32 %0, %1, %2" : "=v"(r) : "v"(lo), "v"(hi)); return r; }
;     __device__ __forceinline__ void operator()(const f32x4 (&acc)[2][2][4][2], const Unit& u, int wr, int wc, int fr, int fq) const {
;     ...
;                 const int row = row0 + ai * HALF + m * 16;
;                 const float* xr = (row < M_P) ? xin_p + (size_t)row * DM : xin_s + (size_t)(row - M_P) * DM;
;                 float* orow = out + (size_t)row * DM;
;                 float ss = 0.f;
; #pragma unroll
;                 for (int bj = 0; bj < 2; ++bj) {
;                     f32x4 o[2];
; #pragma unroll
;                     for (int n = 0; n < 2; ++n) { const f32x4 xv = *(const f32x4*)(xr + col0 + bj * HALF + 4 * n); o[n] = xv + acc[ai][bj][m][n] * (0.5f * ALPHA2); *(f32x4*)(orow + col0 + bj * HALF + 4 * n) = o[n]; }
;                     if constexpr (WX) {
; #pragma unroll
;                         for (int n = 0; n < 2; ++n) ss += (o[n][0] * o[n][0] + o[n][1] * o[n][1]) + (o[n][2] * o[n][2] + o[n][3] * o[n][3]);
;                         const f32x4 a = o[0] * gv[bj][0], b = o[1] * gv[bj][1];
;                         u32x4 w; w.x = cvt_pk_bf16(a[0], a[1]); w.y = cvt_pk_bf16(a[2], a[3]); w.z = cvt_pk_bf16(b[0], b[1]); w.w = cvt_pk_bf16(b[2], b[3]);
;                         *(u32x4*)(xn + (size_t)row * DM + col0 + bj * HALF) = w;
;                     }
;                 }
;                 if constexpr (WX) { ss += __shfl_xor(ss, 16); ss += __shfl_xor(ss, 32); if (fq == 0) ssq[((size_t)u.pn * MROWS + row) * 4 + wc] = ss; }
.LBB0_1078:
	s_or_b64 exec, exec, s[16:17]
	s_waitcnt lgkmcnt(0)
	v_add_u32_e32 v32, 0xa0, v164
	v_cmp_lt_i32_e32 vcc, s70, v164
	s_and_saveexec_b64 s[16:17], vcc
	s_xor_b64 s[16:17], exec, s[16:17]
	v_add_u32_e32 v152, 0xffffc0a0, v164
	v_lshlrev_b64 v[34:35], 12, v[152:153]
	v_lshl_add_u64 v[34:35], s[10:11], 0, v[34:35]
	v_mov_b32_e32 v33, v153
	s_andn2_saveexec_b64 s[16:17], s[16:17]
	v_ashrrev_i32_e32 v33, 31, v32
	v_lshlrev_b64 v[34:35], 12, v[32:33]
	v_lshl_add_u64 v[34:35], s[22:23], 0, v[34:35]
	s_or_b64 exec, exec, s[16:17]
	v_lshl_add_u64 v[38:39], v[34:35], 0, v[166:167]
	s_nop 0
	v_lshlrev_b64 v[40:41], 12, v[32:33]
	v_lshl_add_u64 v[40:41], s[22:23], 0, v[40:41]
	v_lshl_add_u64 v[40:41], v[40:41], 0, v[166:167]
	v_lshlrev_b64 v[42:43], 11, v[32:33]
	v_lshl_add_u64 v[42:43], s[20:21], 0, v[42:43]
	v_lshl_add_u64 v[42:43], v[162:163], 1, v[42:43]
	s_waitcnt vmcnt(25)
	v_pk_add_f32 v[30:31], v[30:31], v[194:195]
	v_pk_add_f32 v[28:29], v[28:29], v[192:193]
	global_store_dwordx4 v[40:41], v[28:31], off
	s_nop 0
	v_pk_mul_f32 v[44:45], v[78:79], v[30:31]
	v_pk_mul_f32 v[46:47], v[76:77], v[28:29]
	v_mul_f32_e32 v29, v29, v29
	v_mul_f32_e32 v31, v31, v31
	v_fmac_f32_e32 v29, v28, v28
	v_fmac_f32_e32 v31, v30, v30
	v_add_f32_e32 v28, v29, v31
	s_waitcnt vmcnt(24)
	v_pk_add_f32 v[24:25], v[24:25], v[196:197]
	v_pk_add_f32 v[26:27], v[26:27], v[198:199]
	v_pk_mul_f32 v[36:37], v[68:69], v[24:25]
	global_store_dwordx4 v[40:41], v[24:27], off offset:16
	v_pk_mul_f32 v[48:49], v[70:71], v[26:27]
	v_cvt_pk_bf16_f32 v34, v46, v47
	v_cvt_pk_bf16_f32 v35, v44, v45
	v_cvt_pk_bf16_f32 v36, v36, v37
	s_nop 0
	v_cvt_pk_bf16_f32 v37, v48, v49
	global_store_dwordx4 v[42:43], v[34:37], off
	s_nop 0
	v_mul_f32_e32 v25, v25, v25
	v_mul_f32_e32 v27, v27, v27
	v_fmac_f32_e32 v25, v24, v24
	v_fmac_f32_e32 v27, v26, v26
	v_add_f32_e32 v24, v25, v27
	v_add_f32_e32 v24, v28, v24
	s_waitcnt vmcnt(23)
	v_pk_add_f32 v[22:23], v[22:23], v[202:203]
	v_pk_add_f32 v[20:21], v[20:21], v[200:201]
	global_store_dwordx4 v[40:41], v[20:23], off offset:512
	s_nop 0
	v_mul_f32_e32 v25, v21, v21
	v_mul_f32_e32 v26, v23, v23
	v_fmac_f32_e32 v25, v20, v20
	v_fmac_f32_e32 v26, v22, v22
	v_add_f32_e32 v25, v25, v26
	v_add_f32_e32 v24, v24, v25
	v_pk_mul_f32 v[20:21], v[60:61], v[20:21]
	v_pk_mul_f32 v[22:23], v[62:63], v[22:23]
	s_waitcnt vmcnt(22)
	v_pk_add_f32 v[18:19], v[18:19], v[206:207]
	v_pk_add_f32 v[16:17], v[16:17], v[204:205]
	v_mul_f32_e32 v26, v19, v19
	v_mul_f32_e32 v25, v17, v17
	v_fmac_f32_e32 v25, v16, v16
	v_fmac_f32_e32 v26, v18, v18
	v_add_f32_e32 v25, v25, v26
	v_add_f32_e32 v28, v24, v25
	ds_bpermute_b32 v29, v211, v28
	global_store_dwordx4 v[40:41], v[16:19], off offset:528
	v_pk_mul_f32 v[26:27], v[56:57], v[16:17]
	v_pk_mul_f32 v[24:25], v[58:59], v[18:19]
	v_cvt_pk_bf16_f32 v18, v20, v21
	s_waitcnt lgkmcnt(0)
	v_add_f32_e32 v16, v28, v29
	ds_bpermute_b32 v17, v212, v16
	v_cvt_pk_bf16_f32 v19, v22, v23
	v_cvt_pk_bf16_f32 v20, v26, v27
	v_cvt_pk_bf16_f32 v21, v24, v25
	global_store_dwordx4 v[42:43], v[18:21], off offset:256
	s_and_saveexec_b64 s[16:17], s[6:7]
	s_cbranch_execz .LBB0_1084
	v_lshl_add_u64 v[18:19], v[32:33], 0, s[48:49]
	v_lshl_add_u64 v[18:19], v[18:19], 4, s[36:37]
	s_waitcnt lgkmcnt(0)
	v_add_f32_e32 v16, v16, v17
	global_store_dword v[18:19], v16, off
.LBB0_1084:
	s_or_b64 exec, exec, s[16:17]
	s_waitcnt lgkmcnt(0)
	v_add_u32_e32 v16, 0xb0, v164
	v_cmp_lt_i32_e32 vcc, s71, v164
	s_and_saveexec_b64 s[16:17], vcc
	s_xor_b64 s[16:17], exec, s[16:17]
	v_add_u32_e32 v152, 0xffffc0b0, v164
	v_lshlrev_b64 v[18:19], 12, v[152:153]
	v_lshl_add_u64 v[18:19], s[10:11], 0, v[18:19]
	v_mov_b32_e32 v17, v153
	s_andn2_saveexec_b64 s[16:17], s[16:17]
	v_ashrrev_i32_e32 v17, 31, v16
	v_lshlrev_b64 v[18:19], 12, v[16:17]
	v_lshl_add_u64 v[18:19], s[22:23], 0, v[18:19]
	s_or_b64 exec, exec, s[16:17]
	v_lshl_add_u64 v[22:23], v[18:19], 0, v[166:167]
	s_nop 0
	v_lshlrev_b64 v[24:25], 12, v[16:17]
	v_lshl_add_u64 v[24:25], s[22:23], 0, v[24:25]
	v_lshl_add_u64 v[24:25], v[24:25], 0, v[166:167]
	v_lshlrev_b64 v[26:27], 11, v[16:17]
	v_lshl_add_u64 v[26:27], s[20:21], 0, v[26:27]
	v_lshl_add_u64 v[26:27], v[162:163], 1, v[26:27]
	s_waitcnt vmcnt(21)
	v_pk_add_f32 v[14:15], v[14:15], v[216:217]
	v_pk_add_f32 v[12:13], v[12:13], v[214:215]
	global_store_dwordx4 v[24:25], v[12:15], off
	s_nop 0
	v_pk_mul_f32 v[28:29], v[78:79], v[14:15]
	v_pk_mul_f32 v[30:31], v[76:77], v[12:13]
	v_mul_f32_e32 v13, v13, v13
	v_mul_f32_e32 v15, v15, v15
	v_fmac_f32_e32 v13, v12, v12
	v_fmac_f32_e32 v15, v14, v14
	v_add_f32_e32 v12, v13, v15
	s_waitcnt vmcnt(20)
	v_pk_add_f32 v[8:9], v[8:9], v[218:219]
	v_pk_add_f32 v[10:11], v[10:11], v[220:221]
	v_pk_mul_f32 v[20:21], v[68:69], v[8:9]
	global_store_dwordx4 v[24:25], v[8:11], off offset:16
	v_pk_mul_f32 v[32:33], v[70:71], v[10:11]
	v_cvt_pk_bf16_f32 v18, v30, v31
	v_cvt_pk_bf16_f32 v19, v28, v29
	v_cvt_pk_bf16_f32 v20, v20, v21
	s_nop 0
	v_cvt_pk_bf16_f32 v21, v32, v33
	global_store_dwordx4 v[26:27], v[18:21], off
	s_nop 0
	v_mul_f32_e32 v9, v9, v9
	v_mul_f32_e32 v11, v11, v11
	v_fmac_f32_e32 v9, v8, v8
	v_fmac_f32_e32 v11, v10, v10
	v_add_f32_e32 v8, v9, v11
	v_add_f32_e32 v8, v12, v8
	s_waitcnt vmcnt(19)
	v_pk_add_f32 v[6:7], v[6:7], v[224:225]
	v_pk_add_f32 v[4:5], v[4:5], v[222:223]
	global_store_dwordx4 v[24:25], v[4:7], off offset:512
	s_nop 0
	v_mul_f32_e32 v9, v5, v5
	v_mul_f32_e32 v10, v7, v7
	v_fmac_f32_e32 v9, v4, v4
	v_fmac_f32_e32 v10, v6, v6
	v_add_f32_e32 v9, v9, v10
	v_add_f32_e32 v8, v8, v9
	v_pk_mul_f32 v[4:5], v[60:61], v[4:5]
	v_pk_mul_f32 v[6:7], v[62:63], v[6:7]
	s_waitcnt vmcnt(18)
	v_pk_add_f32 v[2:3], v[2:3], v[228:229]
	v_pk_add_f32 v[0:1], v[0:1], v[226:227]
	v_mul_f32_e32 v10, v3, v3
	v_mul_f32_e32 v9, v1, v1
	v_fmac_f32_e32 v9, v0, v0
	v_fmac_f32_e32 v10, v2, v2
	v_add_f32_e32 v9, v9, v10
	v_add_f32_e32 v12, v8, v9
	ds_bpermute_b32 v13, v211, v12
	global_store_dwordx4 v[24:25], v[0:3], off offset:528
	v_pk_mul_f32 v[10:11], v[56:57], v[0:1]
	v_pk_mul_f32 v[8:9], v[58:59], v[2:3]
	v_cvt_pk_bf16_f32 v2, v4, v5
	s_waitcnt lgkmcnt(0)
	v_add_f32_e32 v0, v12, v13
	ds_bpermute_b32 v1, v212, v0
	v_cvt_pk_bf16_f32 v3, v6, v7
	v_cvt_pk_bf16_f32 v4, v10, v11
	v_cvt_pk_bf16_f32 v5, v8, v9
	global_store_dwordx4 v[26:27], v[2:5], off offset:256
	s_and_saveexec_b64 s[16:17], s[6:7]
	s_cbranch_execz .LBB0_1090
	v_lshl_add_u64 v[2:3], v[16:17], 0, s[48:49]
	v_lshl_add_u64 v[2:3], v[2:3], 4, s[36:37]
	s_waitcnt lgkmcnt(0)
	v_add_f32_e32 v0, v0, v1
	global_store_dword v[2:3], v0, off

; __device__ __forceinline__ unsigned cvt_pk_bf16(float lo, float hi) { unsigned r; asm volatile("v_cvt_pk_bf16_f32 %0, %1, %2" : "=v"(r) : "v"(lo), "v"(hi)); return r; }
; __device__ __forceinline__ float sigmoidf_(float v) { return __builtin_amdgcn_rcpf(1.0f + __builtin_amdgcn_exp2f(-1.4426950408889634f * v)); }
; __device__ __forceinline__ float rstd_of(const float* ssq, int row) {
;     const f32x4* p = (const f32x4*)ssq + row; const f32x4 s = (p[0] + p[MROWS]) + (p[2 * MROWS] + p[3 * MROWS]);
;     return 1.0f / sqrtf(((s[0] + s[1]) + (s[2] + s[3])) * (1.0f / 1024.0f) + RMS_EPS); }
;     __device__ __forceinline__ void operator()(const f32x4 (&acc)[2][2][4][2], const Unit& u, int wr, int wc, int fr, int fq) const {
;         const int row0 = u.pm * BM + wr * 64 + fr, colh = u.pn * 128 + wc * 32 + 8 * fq;
; #pragma unroll
;         for (int ai = 0; ai < 2; ++ai)
; #pragma unroll
;             for (int m = 0; m < 4; ++m) {
;                 const int row = row0 + ai * HALF + m * 16;
;                 const float rs = ssq ? rstd_of(ssq, row) : 1.0f;
;                 float h[8];
; #pragma unroll
;                 for (int n = 0; n < 2; ++n)
; #pragma unroll
;                     for (int e = 0; e < 4; ++e) { const float g = acc[ai][0][m][n][e] * rs, uu = acc[ai][1][m][n][e] * rs; h[n * 4 + e] = g * sigmoidf_(g) * uu; }
;                 u32x4 w; w.x = cvt_pk_bf16(h[0], h[1]); w.y = cvt_pk_bf16(h[2], h[3]); w.z = cvt_pk_bf16(h[4], h[5]); w.w = cvt_pk_bf16(h[6], h[7]);
;                 *(u32x4*)(H + (size_t)row * DFF + colh) = w;
.LBB0_1160:
	v_lshl_add_u32 v144, s8, 8, v149
	v_ashrrev_i32_e32 v145, 31, v144
	v_cndmask_b32_e64 v146, 0, 1, s[84:85]
	v_mov_b32_e32 v148, 1.0
	v_cmp_ne_u32_e64 s[0:1], 1, v146
	s_andn2_b64 vcc, exec, s[84:85]
	v_lshl_add_u64 v[146:147], v[144:145], 4, s[24:25]
	v_mov_b32_e32 v150, 1.0
	s_cbranch_vccnz .LBB0_1162
	v_add_co_u32_e32 v206, vcc, 0xc0000, v146
	s_nop 1
	v_addc_co_u32_e32 v207, vcc, 0, v147, vcc
	v_add_co_u32_e32 v208, vcc, 0x180000, v146
	s_nop 1
	v_addc_co_u32_e32 v209, vcc, 0, v147, vcc
	v_add_co_u32_e32 v238, vcc, 0x240000, v146
	s_nop 1
	v_addc_co_u32_e32 v239, vcc, 0, v147, vcc
	global_load_dwordx4 v[174:177], v[146:147], off
	global_load_dwordx4 v[178:181], v[206:207], off
	global_load_dwordx4 v[182:185], v[208:209], off
	global_load_dwordx4 v[186:189], v[238:239], off
	global_load_dwordx4 v[190:193], v[146:147], off offset:256
	global_load_dwordx4 v[194:197], v[206:207], off offset:256
	global_load_dwordx4 v[198:201], v[208:209], off offset:256
	global_load_dwordx4 v[202:205], v[238:239], off offset:256
	global_load_dwordx4 v[212:215], v[146:147], off offset:512
	global_load_dwordx4 v[216:219], v[206:207], off offset:512
	global_load_dwordx4 v[220:223], v[208:209], off offset:512
	global_load_dwordx4 v[224:227], v[238:239], off offset:512
	s_waitcnt vmcnt(8)
	v_pk_add_f32 v[160:161], v[176:177], v[180:181]
	v_pk_add_f32 v[158:159], v[174:175], v[178:179]
	v_pk_add_f32 v[162:163], v[184:185], v[188:189]
	v_pk_add_f32 v[164:165], v[182:183], v[186:187]
	global_load_dwordx4 v[174:177], v[146:147], off offset:768
	global_load_dwordx4 v[178:181], v[206:207], off offset:768
	global_load_dwordx4 v[182:185], v[208:209], off offset:768
	global_load_dwordx4 v[186:189], v[238:239], off offset:768
	v_pk_add_f32 v[160:161], v[160:161], v[162:163]
	v_pk_add_f32 v[158:159], v[158:159], v[164:165]
	s_nop 0
	v_pk_mov_b32 v[162:163], v[158:159], v[160:161] op_sel:[1,0]
	v_mov_b32_e32 v159, v161
	v_pk_add_f32 v[158:159], v[162:163], v[158:159]
	s_nop 0
	v_add_f32_e32 v145, v158, v159
	v_fmamk_f32 v145, v145, 0x3a800000, v156
	v_rsq_f32_e32 v252, v145
	s_nop 0
	v_mul_f32_e32 v250, v145, v252
	v_fma_f32 v250, -v250, v252, 1.0
	v_mul_f32_e32 v251, 0.5, v252
	v_fma_f32 v150, v251, v250, v252
.LBB0_1162:
	v_mov_b32_e32 v158, v120
	v_mov_b32_e32 v159, v124
	v_pk_mul_f32 v[158:159], v[158:159], v[150:151] op_sel_hi:[1,0]
	v_mov_b32_e32 v124, v121
	v_mul_f32_e32 v120, 0xbfb8aa3b, v159
	v_exp_f32_e32 v145, v120
	v_pk_mul_f32 v[124:125], v[124:125], v[150:151] op_sel_hi:[1,0]
	s_and_b64 vcc, exec, s[0:1]
	v_mul_f32_e32 v120, 0xbfb8aa3b, v125
	v_exp_f32_e32 v121, v120
	v_add_f32_e32 v145, 1.0, v145
	v_rcp_f32_e32 v145, v145
	v_lshl_or_b32 v120, s44, 7, v152
	v_add_f32_e32 v121, 1.0, v121
	v_rcp_f32_e32 v160, v121
	v_mul_f32_e32 v145, v159, v145
	v_mul_f32_e32 v145, v158, v145
	v_mov_b32_e32 v158, v122
	v_mov_b32_e32 v159, v126
	v_pk_mul_f32 v[158:159], v[158:159], v[150:151] op_sel_hi:[1,0]
	v_mov_b32_e32 v126, v123
	v_mul_f32_e32 v122, 0xbfb8aa3b, v159
	v_mul_f32_e32 v125, v125, v160
	v_exp_f32_e32 v160, v122
	v_pk_mul_f32 v[122:123], v[126:127], v[150:151] op_sel_hi:[1,0]
	v_mul_f32_e32 v127, v124, v125
	v_mul_f32_e32 v126, 0xbfb8aa3b, v123
	v_exp_f32_e32 v126, v126
	v_add_f32_e32 v124, 1.0, v160
	v_rcp_f32_e32 v160, v124
	v_mov_b32_e32 v125, v116
	v_add_f32_e32 v124, 1.0, v126
	v_rcp_f32_e32 v126, v124
	v_mov_b32_e32 v124, v112
	v_pk_mul_f32 v[124:125], v[124:125], v[150:151] op_sel_hi:[1,0]
	v_mul_f32_e32 v116, v159, v160
	v_mul_f32_e32 v112, 0xbfb8aa3b, v125
	v_exp_f32_e32 v112, v112
	v_mul_f32_e32 v158, v158, v116
	v_mov_b32_e32 v116, v113
	v_mul_f32_e32 v123, v123, v126
	v_add_f32_e32 v112, 1.0, v112
	v_rcp_f32_e32 v126, v112
	v_pk_mul_f32 v[112:113], v[116:117], v[150:151] op_sel_hi:[1,0]
	v_mul_f32_e32 v122, v122, v123
	v_mul_f32_e32 v116, 0xbfb8aa3b, v113
	v_exp_f32_e32 v116, v116
	v_mul_f32_e32 v117, v125, v126
	v_mul_f32_e32 v123, v124, v117
	v_mov_b32_e32 v117, v118
	v_add_f32_e32 v116, 1.0, v116
	v_rcp_f32_e32 v124, v116
	v_mov_b32_e32 v116, v114
	v_pk_mul_f32 v[116:117], v[116:117], v[150:151] op_sel_hi:[1,0]
	v_mov_b32_e32 v118, v115
	v_mul_f32_e32 v114, 0xbfb8aa3b, v117
	v_exp_f32_e32 v125, v114
	v_pk_mul_f32 v[114:115], v[118:119], v[150:151] op_sel_hi:[1,0]
	v_mul_f32_e32 v113, v113, v124
	v_mul_f32_e32 v118, 0xbfb8aa3b, v115
	v_exp_f32_e32 v118, v118
	v_add_f32_e32 v119, 1.0, v125
	v_rcp_f32_e32 v119, v119
	v_mul_f32_e32 v124, v112, v113
	v_add_f32_e32 v118, 1.0, v118
	v_rcp_f32_e32 v118, v118
	v_mul_f32_e32 v112, v117, v119
	v_mul_f32_e32 v116, v116, v112
	v_ashrrev_i32_e32 v121, 31, v120
	v_mul_f32_e32 v112, v115, v118
	v_mul_f32_e32 v115, v114, v112
	v_cvt_pk_bf16_f32 v112, v145, v127
	v_cvt_pk_bf16_f32 v113, v158, v122
	v_cvt_pk_bf16_f32 v114, v123, v124
	v_cvt_pk_bf16_f32 v115, v116, v115
	v_mov_b64_e32 v[116:117], s[30:31]
	v_mad_i64_i32 v[116:117], s[8:9], v144, s60, v[116:117]
	v_lshl_add_u64 v[116:117], v[120:121], 1, v[116:117]
	global_store_dwordx4 v[116:117], v[112:115], off
	s_cbranch_vccnz .LBB0_1164
	s_waitcnt vmcnt(9)
	v_pk_add_f32 v[114:115], v[192:193], v[196:197]
	v_pk_add_f32 v[112:113], v[190:191], v[194:195]
	v_pk_add_f32 v[116:117], v[200:201], v[204:205]
	v_pk_add_f32 v[118:119], v[198:199], v[202:203]
	global_load_dwordx4 v[190:193], v[146:147], off offset:2048
	global_load_dwordx4 v[194:197], v[206:207], off offset:2048
	global_load_dwordx4 v[198:201], v[208:209], off offset:2048
	global_load_dwordx4 v[202:205], v[238:239], off offset:2048
	v_pk_add_f32 v[114:115], v[114:115], v[116:117]
	v_pk_add_f32 v[112:113], v[112:113], v[118:119]
	s_nop 0
	v_pk_mov_b32 v[116:117], v[112:113], v[114:115] op_sel:[1,0]
	v_mov_b32_e32 v113, v115
	v_pk_add_f32 v[112:113], v[116:117], v[112:113]
	s_nop 0
	v_add_f32_e32 v112, v112, v113
	v_fmamk_f32 v112, v112, 0x3a800000, v156
	v_rsq_f32_e32 v252, v112
	s_nop 0
	v_mul_f32_e32 v250, v112, v252
	v_fma_f32 v250, -v250, v252, 1.0
	v_mul_f32_e32 v251, 0.5, v252
	v_fma_f32 v148, v251, v250, v252
; __device__ __forceinline__ unsigned cvt_pk_bf16(float lo, float hi) { unsigned r; asm volatile("v_cvt_pk_bf16_f32 %0, %1, %2" : "=v"(r) : "v"(lo), "v"(hi)); return r; }
; __device__ __forceinline__ float sigmoidf_(float v) { return __builtin_amdgcn_rcpf(1.0f + __builtin_amdgcn_exp2f(-1.4426950408889634f * v)); }
; __device__ __forceinline__ float rstd_of(const float* ssq, int row) {
;     const f32x4* p = (const f32x4*)ssq + row; const f32x4 s = (p[0] + p[MROWS]) + (p[2 * MROWS] + p[3 * MROWS]);
;     return 1.0f / sqrtf(((s[0] + s[1]) + (s[2] + s[3])) * (1.0f / 1024.0f) + RMS_EPS); }
;     __device__ __forceinline__ void operator()(const f32x4 (&acc)[2][2][4][2], const Unit& u, int wr, int wc, int fr, int fq) const {
;         const int row0 = u.pm * BM + wr * 64 + fr, colh = u.pn * 128 + wc * 32 + 8 * fq;
; #pragma unroll
;         for (int ai = 0; ai < 2; ++ai)
; #pragma unroll
;             for (int m = 0; m < 4; ++m) {
;                 const int row = row0 + ai * HALF + m * 16;
;                 const float rs = ssq ? rstd_of(ssq, row) : 1.0f;
;                 float h[8];
; #pragma unroll
;                 for (int n = 0; n < 2; ++n)
; #pragma unroll
;                     for (int e = 0; e < 4; ++e) { const float g = acc[ai][0][m][n][e] * rs, uu = acc[ai][1][m][n][e] * rs; h[n * 4 + e] = g * sigmoidf_(g) * uu; }
;                 u32x4 w; w.x = cvt_pk_bf16(h[0], h[1]); w.y = cvt_pk_bf16(h[2], h[3]); w.z = cvt_pk_bf16(h[4], h[5]); w.w = cvt_pk_bf16(h[6], h[7]);
;                 *(u32x4*)(H + (size_t)row * DFF + colh) = w;
.LBB0_1164:
	s_nop 0
	v_mov_b32_e32 v112, v104
	v_mov_b32_e32 v113, v108
	v_pk_mul_f32 v[112:113], v[112:113], v[148:149] op_sel_hi:[1,0]
	v_mov_b32_e32 v108, v105
	v_mul_f32_e32 v104, 0xbfb8aa3b, v113
	v_exp_f32_e32 v104, v104
	v_pk_mul_f32 v[108:109], v[108:109], v[148:149] op_sel_hi:[1,0]
	v_or_b32_e32 v114, 16, v144
	v_mul_f32_e32 v105, 0xbfb8aa3b, v109
	v_exp_f32_e32 v105, v105
	v_add_f32_e32 v104, 1.0, v104
	v_rcp_f32_e32 v115, v104
	s_and_b64 vcc, exec, s[0:1]
	v_add_f32_e32 v104, 1.0, v105
	v_rcp_f32_e32 v105, v104
	v_mul_f32_e32 v113, v113, v115
	v_mul_f32_e32 v115, v112, v113
	v_mov_b32_e32 v112, v106
	v_mov_b32_e32 v113, v110
	v_pk_mul_f32 v[112:113], v[112:113], v[148:149] op_sel_hi:[1,0]
	v_mov_b32_e32 v110, v107
	v_mul_f32_e32 v106, 0xbfb8aa3b, v113
	v_mul_f32_e32 v105, v109, v105
	v_exp_f32_e32 v109, v106
	v_pk_mul_f32 v[106:107], v[110:111], v[148:149] op_sel_hi:[1,0]
	v_mul_f32_e32 v105, v108, v105
	v_mul_f32_e32 v110, 0xbfb8aa3b, v107
	v_exp_f32_e32 v110, v110
	v_add_f32_e32 v108, 1.0, v109
	v_rcp_f32_e32 v111, v108
	v_mov_b32_e32 v109, v100
	v_add_f32_e32 v108, 1.0, v110
	v_rcp_f32_e32 v110, v108
	v_mov_b32_e32 v108, v96
	v_pk_mul_f32 v[108:109], v[108:109], v[148:149] op_sel_hi:[1,0]
	v_mul_f32_e32 v100, v113, v111
	v_mul_f32_e32 v96, 0xbfb8aa3b, v109
	v_exp_f32_e32 v96, v96
	v_mul_f32_e32 v111, v112, v100
	v_mov_b32_e32 v100, v97
	v_mul_f32_e32 v107, v107, v110
	v_add_f32_e32 v96, 1.0, v96
	v_rcp_f32_e32 v110, v96
	v_pk_mul_f32 v[96:97], v[100:101], v[148:149] op_sel_hi:[1,0]
	v_mul_f32_e32 v106, v106, v107
	v_mul_f32_e32 v100, 0xbfb8aa3b, v97
	v_exp_f32_e32 v100, v100
	v_mul_f32_e32 v101, v109, v110
	v_mul_f32_e32 v107, v108, v101
	v_mov_b32_e32 v101, v102
	v_add_f32_e32 v100, 1.0, v100
	v_rcp_f32_e32 v108, v100
	v_mov_b32_e32 v100, v98
	v_pk_mul_f32 v[100:101], v[100:101], v[148:149] op_sel_hi:[1,0]
	v_mov_b32_e32 v102, v99
	v_mul_f32_e32 v98, 0xbfb8aa3b, v101
	v_exp_f32_e32 v109, v98
	v_pk_mul_f32 v[98:99], v[102:103], v[148:149] op_sel_hi:[1,0]
	v_mul_f32_e32 v97, v97, v108
	v_mul_f32_e32 v102, 0xbfb8aa3b, v99
	v_exp_f32_e32 v102, v102
	v_add_f32_e32 v103, 1.0, v109
	v_rcp_f32_e32 v103, v103
	v_mul_f32_e32 v108, v96, v97
	v_add_f32_e32 v102, 1.0, v102
	v_rcp_f32_e32 v102, v102
	v_mul_f32_e32 v96, v101, v103
	v_mul_f32_e32 v100, v100, v96
	v_mov_b32_e32 v104, 1.0
	v_mul_f32_e32 v96, v99, v102
	v_mul_f32_e32 v99, v98, v96
	v_cvt_pk_bf16_f32 v96, v115, v105
	v_cvt_pk_bf16_f32 v97, v111, v106
	v_cvt_pk_bf16_f32 v98, v107, v108
	v_cvt_pk_bf16_f32 v99, v100, v99
	v_mov_b64_e32 v[100:101], s[30:31]
	v_mad_i64_i32 v[100:101], s[8:9], v114, s60, v[100:101]
	v_lshl_add_u64 v[100:101], v[120:121], 1, v[100:101]
	global_store_dwordx4 v[100:101], v[96:99], off
	s_nop 1
	v_mov_b32_e32 v96, 1.0
	s_cbranch_vccnz .LBB0_1166
	s_waitcnt vmcnt(10)
	v_pk_add_f32 v[98:99], v[214:215], v[218:219]
	v_pk_add_f32 v[96:97], v[212:213], v[216:217]
	v_pk_add_f32 v[100:101], v[222:223], v[226:227]
	v_pk_add_f32 v[102:103], v[220:221], v[224:225]
	global_load_dwordx4 v[212:215], v[146:147], off offset:2304
	global_load_dwordx4 v[216:219], v[206:207], off offset:2304
	global_load_dwordx4 v[220:223], v[208:209], off offset:2304
	global_load_dwordx4 v[224:227], v[238:239], off offset:2304
	v_pk_add_f32 v[98:99], v[98:99], v[100:101]
	v_pk_add_f32 v[96:97], v[96:97], v[102:103]
	s_nop 0
	v_pk_mov_b32 v[100:101], v[96:97], v[98:99] op_sel:[1,0]
	v_mov_b32_e32 v97, v99
	v_pk_add_f32 v[96:97], v[100:101], v[96:97]
	s_nop 0
	v_add_f32_e32 v96, v96, v97
	v_fmamk_f32 v96, v96, 0x3a800000, v156
	v_rsq_f32_e32 v252, v96
	s_nop 0
	v_mul_f32_e32 v250, v96, v252
	v_fma_f32 v250, -v250, v252, 1.0
	v_mul_f32_e32 v251, 0.5, v252
	v_fma_f32 v96, v251, v250, v252
.LBB0_1166:
	v_mov_b32_e32 v98, v88
	v_mov_b32_e32 v99, v92
	v_pk_mul_f32 v[98:99], v[98:99], v[96:97] op_sel_hi:[1,0]
	v_mov_b32_e32 v92, v89
	v_mul_f32_e32 v88, 0xbfb8aa3b, v99
	v_exp_f32_e32 v97, v88
	s_and_b64 vcc, exec, s[0:1]
	v_pk_mul_f32 v[88:89], v[92:93], v[96:97] op_sel_hi:[1,0]
	s_nop 0
	v_mul_f32_e32 v92, 0xbfb8aa3b, v89
	v_exp_f32_e32 v92, v92
	v_add_f32_e32 v93, 1.0, v97
	v_rcp_f32_e32 v93, v93
	v_or_b32_e32 v97, 32, v144
	v_add_f32_e32 v92, 1.0, v92
	v_rcp_f32_e32 v92, v92
	v_mul_f32_e32 v93, v99, v93
	v_mul_f32_e32 v98, v98, v93
	v_mov_b32_e32 v93, v94
	v_mul_f32_e32 v89, v89, v92
	v_mov_b32_e32 v92, v90
	v_pk_mul_f32 v[92:93], v[92:93], v[96:97] op_sel_hi:[1,0]
	v_mov_b32_e32 v94, v91
	v_mul_f32_e32 v90, 0xbfb8aa3b, v93
	v_exp_f32_e32 v99, v90
	v_pk_mul_f32 v[90:91], v[94:95], v[96:97] op_sel_hi:[1,0]
	v_mul_f32_e32 v95, v88, v89
	v_mul_f32_e32 v94, 0xbfb8aa3b, v91
	v_exp_f32_e32 v94, v94
	v_add_f32_e32 v88, 1.0, v99
	v_rcp_f32_e32 v99, v88
	v_mov_b32_e32 v89, v84
	v_add_f32_e32 v88, 1.0, v94
	v_rcp_f32_e32 v94, v88
	v_mov_b32_e32 v88, v80
	v_pk_mul_f32 v[88:89], v[88:89], v[96:97] op_sel_hi:[1,0]
	v_mul_f32_e32 v84, v93, v99
	v_mul_f32_e32 v80, 0xbfb8aa3b, v89
	v_exp_f32_e32 v80, v80
	v_mul_f32_e32 v92, v92, v84
	v_mov_b32_e32 v84, v81
	v_mul_f32_e32 v91, v91, v94
	v_add_f32_e32 v80, 1.0, v80
	v_rcp_f32_e32 v93, v80
	v_pk_mul_f32 v[80:81], v[84:85], v[96:97] op_sel_hi:[1,0]
	v_mul_f32_e32 v90, v90, v91
	v_mul_f32_e32 v84, 0xbfb8aa3b, v81
	v_exp_f32_e32 v84, v84
	v_mul_f32_e32 v85, v89, v93
	v_mul_f32_e32 v88, v88, v85
	v_mov_b32_e32 v85, v86
	v_add_f32_e32 v84, 1.0, v84
	v_rcp_f32_e32 v89, v84
	v_mov_b32_e32 v84, v82
	v_pk_mul_f32 v[84:85], v[84:85], v[96:97] op_sel_hi:[1,0]
	v_mov_b32_e32 v86, v83
	v_mul_f32_e32 v82, 0xbfb8aa3b, v85
	v_exp_f32_e32 v91, v82
	v_pk_mul_f32 v[82:83], v[86:87], v[96:97] op_sel_hi:[1,0]
	v_mul_f32_e32 v81, v81, v89
	v_mul_f32_e32 v86, 0xbfb8aa3b, v83
	v_exp_f32_e32 v86, v86
	v_add_f32_e32 v87, 1.0, v91
	v_rcp_f32_e32 v87, v87
	v_mul_f32_e32 v89, v80, v81
	v_add_f32_e32 v86, 1.0, v86
	v_rcp_f32_e32 v86, v86
	v_mul_f32_e32 v80, v85, v87
	v_mul_f32_e32 v84, v84, v80
	v_mul_f32_e32 v80, v83, v86
	v_mul_f32_e32 v83, v82, v80
	v_cvt_pk_bf16_f32 v80, v98, v95
	v_cvt_pk_bf16_f32 v81, v92, v90
	v_cvt_pk_bf16_f32 v82, v88, v89
	v_cvt_pk_bf16_f32 v83, v84, v83
	v_mov_b64_e32 v[84:85], s[30:31]
	v_mad_i64_i32 v[84:85], s[8:9], v97, s60, v[84:85]
	v_lshl_add_u64 v[84:85], v[120:121], 1, v[84:85]
	global_store_dwordx4 v[84:85], v[80:83], off
	s_cbranch_vccnz .LBB0_1168
; __device__ __forceinline__ unsigned cvt_pk_bf16(float lo, float hi) { unsigned r; asm volatile("v_cvt_pk_bf16_f32 %0, %1, %2" : "=v"(r) : "v"(lo), "v"(hi)); return r; }
; __device__ __forceinline__ float sigmoidf_(float v) { return __builtin_amdgcn_rcpf(1.0f + __builtin_amdgcn_exp2f(-1.4426950408889634f * v)); }
; __device__ __forceinline__ float rstd_of(const float* ssq, int row) {
;     const f32x4* p = (const f32x4*)ssq + row; const f32x4 s = (p[0] + p[MROWS]) + (p[2 * MROWS] + p[3 * MROWS]);
;     return 1.0f / sqrtf(((s[0] + s[1]) + (s[2] + s[3])) * (1.0f / 1024.0f) + RMS_EPS); }
;     __device__ __forceinline__ void operator()(const f32x4 (&acc)[2][2][4][2], const Unit& u, int wr, int wc, int fr, int fq) const {
;         const int row0 = u.pm * BM + wr * 64 + fr, colh = u.pn * 128 + wc * 32 + 8 * fq;
; #pragma unroll
;         for (int ai = 0; ai < 2; ++ai)
; #pragma unroll
;             for (int m = 0; m < 4; ++m) {
;                 const int row = row0 + ai * HALF + m * 16;
;                 const float rs = ssq ? rstd_of(ssq, row) : 1.0f;
;                 float h[8];
; #pragma unroll
;                 for (int n = 0; n < 2; ++n)
; #pragma unroll
;                     for (int e = 0; e < 4; ++e) { const float g = acc[ai][0][m][n][e] * rs, uu = acc[ai][1][m][n][e] * rs; h[n * 4 + e] = g * sigmoidf_(g) * uu; }
;                 u32x4 w; w.x = cvt_pk_bf16(h[0], h[1]); w.y = cvt_pk_bf16(h[2], h[3]); w.z = cvt_pk_bf16(h[4], h[5]); w.w = cvt_pk_bf16(h[6], h[7]);
;                 *(u32x4*)(H + (size_t)row * DFF + colh) = w;
	s_waitcnt vmcnt(11)
	v_pk_add_f32 v[82:83], v[176:177], v[180:181]
	v_pk_add_f32 v[80:81], v[174:175], v[178:179]
	v_pk_add_f32 v[84:85], v[184:185], v[188:189]
	v_pk_add_f32 v[86:87], v[182:183], v[186:187]
	global_load_dwordx4 v[174:177], v[146:147], off offset:2560
	global_load_dwordx4 v[178:181], v[206:207], off offset:2560
	global_load_dwordx4 v[182:185], v[208:209], off offset:2560
	global_load_dwordx4 v[186:189], v[238:239], off offset:2560
	v_pk_add_f32 v[82:83], v[82:83], v[84:85]
	v_pk_add_f32 v[80:81], v[80:81], v[86:87]
	s_nop 0
	v_pk_mov_b32 v[84:85], v[80:81], v[82:83] op_sel:[1,0]
	v_mov_b32_e32 v81, v83
	v_pk_add_f32 v[80:81], v[84:85], v[80:81]
	s_nop 0
	v_add_f32_e32 v80, v80, v81
	v_fmamk_f32 v80, v80, 0x3a800000, v156
	v_rsq_f32_e32 v252, v80
	s_nop 0
	v_mul_f32_e32 v250, v80, v252
	v_fma_f32 v250, -v250, v252, 1.0
	v_mul_f32_e32 v251, 0.5, v252
	v_fma_f32 v104, v251, v250, v252
.LBB0_1168:
	s_nop 0
	v_mov_b32_e32 v80, v72
	v_mov_b32_e32 v81, v76
	v_pk_mul_f32 v[80:81], v[80:81], v[104:105] op_sel_hi:[1,0]
	v_mov_b32_e32 v76, v73
	v_mul_f32_e32 v72, 0xbfb8aa3b, v81
	v_exp_f32_e32 v72, v72
	v_pk_mul_f32 v[76:77], v[76:77], v[104:105] op_sel_hi:[1,0]
	v_or_b32_e32 v82, 48, v144
	v_mul_f32_e32 v73, 0xbfb8aa3b, v77
	v_exp_f32_e32 v73, v73
	v_add_f32_e32 v72, 1.0, v72
	v_rcp_f32_e32 v83, v72
	s_and_b64 vcc, exec, s[0:1]
	v_add_f32_e32 v72, 1.0, v73
	v_rcp_f32_e32 v73, v72
	v_mul_f32_e32 v81, v81, v83
	v_mul_f32_e32 v83, v80, v81
	v_mov_b32_e32 v80, v74
	v_mov_b32_e32 v81, v78
	v_pk_mul_f32 v[80:81], v[80:81], v[104:105] op_sel_hi:[1,0]
	v_mov_b32_e32 v78, v75
	v_mul_f32_e32 v74, 0xbfb8aa3b, v81
	v_mul_f32_e32 v73, v77, v73
	v_exp_f32_e32 v77, v74
	v_pk_mul_f32 v[74:75], v[78:79], v[104:105] op_sel_hi:[1,0]
	v_mul_f32_e32 v73, v76, v73
	v_mul_f32_e32 v78, 0xbfb8aa3b, v75
	v_exp_f32_e32 v78, v78
	v_add_f32_e32 v76, 1.0, v77
	v_rcp_f32_e32 v79, v76
	v_mov_b32_e32 v77, v68
	v_add_f32_e32 v76, 1.0, v78
	v_rcp_f32_e32 v78, v76
	v_mov_b32_e32 v76, v64
	v_pk_mul_f32 v[76:77], v[76:77], v[104:105] op_sel_hi:[1,0]
	v_mul_f32_e32 v68, v81, v79
	v_mul_f32_e32 v64, 0xbfb8aa3b, v77
	v_exp_f32_e32 v64, v64
	v_mul_f32_e32 v79, v80, v68
	v_mov_b32_e32 v68, v65
	v_mul_f32_e32 v75, v75, v78
	v_add_f32_e32 v64, 1.0, v64
	v_rcp_f32_e32 v78, v64
	v_pk_mul_f32 v[64:65], v[68:69], v[104:105] op_sel_hi:[1,0]
	v_mul_f32_e32 v74, v74, v75
	v_mul_f32_e32 v68, 0xbfb8aa3b, v65
	v_exp_f32_e32 v68, v68
	v_mul_f32_e32 v69, v77, v78
	v_mul_f32_e32 v75, v76, v69
	v_mov_b32_e32 v69, v70
	v_add_f32_e32 v68, 1.0, v68
	v_rcp_f32_e32 v76, v68
	v_mov_b32_e32 v68, v66
	v_pk_mul_f32 v[68:69], v[68:69], v[104:105] op_sel_hi:[1,0]
	v_mov_b32_e32 v70, v67
	v_mul_f32_e32 v66, 0xbfb8aa3b, v69
	v_exp_f32_e32 v77, v66
	v_pk_mul_f32 v[66:67], v[70:71], v[104:105] op_sel_hi:[1,0]
	v_mul_f32_e32 v65, v65, v76
	v_mul_f32_e32 v70, 0xbfb8aa3b, v67
	v_exp_f32_e32 v70, v70
	v_add_f32_e32 v71, 1.0, v77
	v_rcp_f32_e32 v71, v71
	v_mul_f32_e32 v76, v64, v65
	v_add_f32_e32 v70, 1.0, v70
	v_rcp_f32_e32 v70, v70
	v_mul_f32_e32 v64, v69, v71
	v_mul_f32_e32 v68, v68, v64
	v_mov_b32_e32 v72, 1.0
	v_mul_f32_e32 v64, v67, v70
	v_mul_f32_e32 v67, v66, v64
	v_cvt_pk_bf16_f32 v64, v83, v73
	v_cvt_pk_bf16_f32 v65, v79, v74
	v_cvt_pk_bf16_f32 v66, v75, v76
	v_cvt_pk_bf16_f32 v67, v68, v67
	v_mov_b64_e32 v[68:69], s[30:31]
	v_mad_i64_i32 v[68:69], s[8:9], v82, s60, v[68:69]
	v_lshl_add_u64 v[68:69], v[120:121], 1, v[68:69]
	global_store_dwordx4 v[68:69], v[64:67], off
	s_nop 1
	v_mov_b32_e32 v64, 1.0
	s_cbranch_vccnz .LBB0_1170
	s_waitcnt vmcnt(11)
	v_pk_add_f32 v[66:67], v[192:193], v[196:197]
	v_pk_add_f32 v[64:65], v[190:191], v[194:195]
	v_pk_add_f32 v[68:69], v[200:201], v[204:205]
	v_pk_add_f32 v[70:71], v[198:199], v[202:203]
	global_load_dwordx4 v[190:193], v[146:147], off offset:2816
	global_load_dwordx4 v[194:197], v[206:207], off offset:2816
	global_load_dwordx4 v[198:201], v[208:209], off offset:2816
	global_load_dwordx4 v[202:205], v[238:239], off offset:2816
	v_pk_add_f32 v[66:67], v[66:67], v[68:69]
	v_pk_add_f32 v[64:65], v[64:65], v[70:71]
	s_nop 0
	v_pk_mov_b32 v[68:69], v[64:65], v[66:67] op_sel:[1,0]
	v_mov_b32_e32 v65, v67
	v_pk_add_f32 v[64:65], v[68:69], v[64:65]
	s_nop 0
	v_add_f32_e32 v64, v64, v65
	v_fmamk_f32 v64, v64, 0x3a800000, v156
	v_rsq_f32_e32 v252, v64
	s_nop 0
	v_mul_f32_e32 v250, v64, v252
	v_fma_f32 v250, -v250, v252, 1.0
	v_mul_f32_e32 v251, 0.5, v252
	v_fma_f32 v64, v251, v250, v252
; __device__ __forceinline__ unsigned cvt_pk_bf16(float lo, float hi) { unsigned r; asm volatile("v_cvt_pk_bf16_f32 %0, %1, %2" : "=v"(r) : "v"(lo), "v"(hi)); return r; }
; __device__ __forceinline__ float sigmoidf_(float v) { return __builtin_amdgcn_rcpf(1.0f + __builtin_amdgcn_exp2f(-1.4426950408889634f * v)); }
; __device__ __forceinline__ float rstd_of(const float* ssq, int row) {
;     const f32x4* p = (const f32x4*)ssq + row; const f32x4 s = (p[0] + p[MROWS]) + (p[2 * MROWS] + p[3 * MROWS]);
;     return 1.0f / sqrtf(((s[0] + s[1]) + (s[2] + s[3])) * (1.0f / 1024.0f) + RMS_EPS); }
;     __device__ __forceinline__ void operator()(const f32x4 (&acc)[2][2][4][2], const Unit& u, int wr, int wc, int fr, int fq) const {
;         const int row0 = u.pm * BM + wr * 64 + fr, colh = u.pn * 128 + wc * 32 + 8 * fq;
; #pragma unroll
;         for (int ai = 0; ai < 2; ++ai)
; #pragma unroll
;             for (int m = 0; m < 4; ++m) {
;                 const int row = row0 + ai * HALF + m * 16;
;                 const float rs = ssq ? rstd_of(ssq, row) : 1.0f;
;                 float h[8];
; #pragma unroll
;                 for (int n = 0; n < 2; ++n)
; #pragma unroll
;                     for (int e = 0; e < 4; ++e) { const float g = acc[ai][0][m][n][e] * rs, uu = acc[ai][1][m][n][e] * rs; h[n * 4 + e] = g * sigmoidf_(g) * uu; }
;                 u32x4 w; w.x = cvt_pk_bf16(h[0], h[1]); w.y = cvt_pk_bf16(h[2], h[3]); w.z = cvt_pk_bf16(h[4], h[5]); w.w = cvt_pk_bf16(h[6], h[7]);
;                 *(u32x4*)(H + (size_t)row * DFF + colh) = w;
.LBB0_1170:
	v_mov_b32_e32 v66, v56
	v_mov_b32_e32 v67, v60
	v_pk_mul_f32 v[66:67], v[66:67], v[64:65] op_sel_hi:[1,0]
	v_mov_b32_e32 v60, v57
	v_mul_f32_e32 v56, 0xbfb8aa3b, v67
	v_exp_f32_e32 v65, v56
	s_and_b64 vcc, exec, s[0:1]
	v_pk_mul_f32 v[56:57], v[60:61], v[64:65] op_sel_hi:[1,0]
	s_nop 0
	v_mul_f32_e32 v60, 0xbfb8aa3b, v57
	v_exp_f32_e32 v60, v60
	v_add_f32_e32 v61, 1.0, v65
	v_rcp_f32_e32 v61, v61
	v_add_u32_e32 v65, 0x80, v144
	v_add_f32_e32 v60, 1.0, v60
	v_rcp_f32_e32 v60, v60
	v_mul_f32_e32 v61, v67, v61
	v_mul_f32_e32 v66, v66, v61
	v_mov_b32_e32 v61, v62
	v_mul_f32_e32 v57, v57, v60
	v_mov_b32_e32 v60, v58
	v_pk_mul_f32 v[60:61], v[60:61], v[64:65] op_sel_hi:[1,0]
	v_mov_b32_e32 v62, v59
	v_mul_f32_e32 v58, 0xbfb8aa3b, v61
	v_exp_f32_e32 v67, v58
	v_pk_mul_f32 v[58:59], v[62:63], v[64:65] op_sel_hi:[1,0]
	v_mul_f32_e32 v63, v56, v57
	v_mul_f32_e32 v62, 0xbfb8aa3b, v59
	v_exp_f32_e32 v62, v62
	v_add_f32_e32 v56, 1.0, v67
	v_rcp_f32_e32 v67, v56
	v_mov_b32_e32 v57, v52
	v_add_f32_e32 v56, 1.0, v62
	v_rcp_f32_e32 v62, v56
	v_mov_b32_e32 v56, v48
	v_pk_mul_f32 v[56:57], v[56:57], v[64:65] op_sel_hi:[1,0]
	v_mul_f32_e32 v52, v61, v67
	v_mul_f32_e32 v48, 0xbfb8aa3b, v57
	v_exp_f32_e32 v48, v48
	v_mul_f32_e32 v60, v60, v52
	v_mov_b32_e32 v52, v49
	v_mul_f32_e32 v59, v59, v62
	v_add_f32_e32 v48, 1.0, v48
	v_rcp_f32_e32 v61, v48
	v_pk_mul_f32 v[48:49], v[52:53], v[64:65] op_sel_hi:[1,0]
	v_mul_f32_e32 v58, v58, v59
	v_mul_f32_e32 v52, 0xbfb8aa3b, v49
	v_exp_f32_e32 v52, v52
	v_mul_f32_e32 v53, v57, v61
	v_mul_f32_e32 v56, v56, v53
	v_mov_b32_e32 v53, v54
	v_add_f32_e32 v52, 1.0, v52
	v_rcp_f32_e32 v57, v52
	v_mov_b32_e32 v52, v50
	v_pk_mul_f32 v[52:53], v[52:53], v[64:65] op_sel_hi:[1,0]
	v_mov_b32_e32 v54, v51
	v_mul_f32_e32 v50, 0xbfb8aa3b, v53
	v_exp_f32_e32 v59, v50
	v_pk_mul_f32 v[50:51], v[54:55], v[64:65] op_sel_hi:[1,0]
	v_mul_f32_e32 v49, v49, v57
	v_mul_f32_e32 v54, 0xbfb8aa3b, v51
	v_exp_f32_e32 v54, v54
	v_add_f32_e32 v55, 1.0, v59
	v_rcp_f32_e32 v55, v55
	v_mul_f32_e32 v57, v48, v49
	v_add_f32_e32 v54, 1.0, v54
	v_rcp_f32_e32 v54, v54
	v_mul_f32_e32 v48, v53, v55
	v_mul_f32_e32 v52, v52, v48
	v_mul_f32_e32 v48, v51, v54
	v_mul_f32_e32 v51, v50, v48
	v_cvt_pk_bf16_f32 v48, v66, v63
	v_cvt_pk_bf16_f32 v49, v60, v58
	v_cvt_pk_bf16_f32 v50, v56, v57
	v_cvt_pk_bf16_f32 v51, v52, v51
	v_mov_b64_e32 v[52:53], s[30:31]
	v_mad_i64_i32 v[52:53], s[8:9], v65, s60, v[52:53]
	v_lshl_add_u64 v[52:53], v[120:121], 1, v[52:53]
	global_store_dwordx4 v[52:53], v[48:51], off
	s_cbranch_vccnz .LBB0_1172
	s_waitcnt vmcnt(11)
	v_pk_add_f32 v[50:51], v[214:215], v[218:219]
	v_pk_add_f32 v[48:49], v[212:213], v[216:217]
	v_pk_add_f32 v[52:53], v[222:223], v[226:227]
	v_pk_add_f32 v[54:55], v[220:221], v[224:225]
	v_pk_add_f32 v[50:51], v[50:51], v[52:53]
	v_pk_add_f32 v[48:49], v[48:49], v[54:55]
	s_nop 0
	v_pk_mov_b32 v[52:53], v[48:49], v[50:51] op_sel:[1,0]
	v_mov_b32_e32 v49, v51
	v_pk_add_f32 v[48:49], v[52:53], v[48:49]
	s_nop 0
	v_add_f32_e32 v48, v48, v49
	v_fmamk_f32 v48, v48, 0x3a800000, v156
	v_rsq_f32_e32 v252, v48
	s_nop 0
	v_mul_f32_e32 v250, v48, v252
	v_fma_f32 v250, -v250, v252, 1.0
	v_mul_f32_e32 v251, 0.5, v252
	v_fma_f32 v72, v251, v250, v252
; __device__ __forceinline__ unsigned cvt_pk_bf16(float lo, float hi) { unsigned r; asm volatile("v_cvt_pk_bf16_f32 %0, %1, %2" : "=v"(r) : "v"(lo), "v"(hi)); return r; }
; __device__ __forceinline__ float sigmoidf_(float v) { return __builtin_amdgcn_rcpf(1.0f + __builtin_amdgcn_exp2f(-1.4426950408889634f * v)); }
; __device__ __forceinline__ float rstd_of(const float* ssq, int row) {
;     const f32x4* p = (const f32x4*)ssq + row; const f32x4 s = (p[0] + p[MROWS]) + (p[2 * MROWS] + p[3 * MROWS]);
;     return 1.0f / sqrtf(((s[0] + s[1]) + (s[2] + s[3])) * (1.0f / 1024.0f) + RMS_EPS); }
;     __device__ __forceinline__ void operator()(const f32x4 (&acc)[2][2][4][2], const Unit& u, int wr, int wc, int fr, int fq) const {
;         const int row0 = u.pm * BM + wr * 64 + fr, colh = u.pn * 128 + wc * 32 + 8 * fq;
; #pragma unroll
;         for (int ai = 0; ai < 2; ++ai)
; #pragma unroll
;             for (int m = 0; m < 4; ++m) {
;                 const int row = row0 + ai * HALF + m * 16;
;                 const float rs = ssq ? rstd_of(ssq, row) : 1.0f;
;                 float h[8];
; #pragma unroll
;                 for (int n = 0; n < 2; ++n)
; #pragma unroll
;                     for (int e = 0; e < 4; ++e) { const float g = acc[ai][0][m][n][e] * rs, uu = acc[ai][1][m][n][e] * rs; h[n * 4 + e] = g * sigmoidf_(g) * uu; }
;                 u32x4 w; w.x = cvt_pk_bf16(h[0], h[1]); w.y = cvt_pk_bf16(h[2], h[3]); w.z = cvt_pk_bf16(h[4], h[5]); w.w = cvt_pk_bf16(h[6], h[7]);
;                 *(u32x4*)(H + (size_t)row * DFF + colh) = w;
.LBB0_1172:
	s_nop 0
	v_mov_b32_e32 v48, v40
	v_mov_b32_e32 v49, v44
	v_pk_mul_f32 v[48:49], v[48:49], v[72:73] op_sel_hi:[1,0]
	v_mov_b32_e32 v44, v41
	v_mul_f32_e32 v40, 0xbfb8aa3b, v49
	v_exp_f32_e32 v40, v40
	v_pk_mul_f32 v[44:45], v[44:45], v[72:73] op_sel_hi:[1,0]
	v_add_u32_e32 v50, 0x90, v144
	v_mul_f32_e32 v41, 0xbfb8aa3b, v45
	v_exp_f32_e32 v41, v41
	v_add_f32_e32 v40, 1.0, v40
	v_rcp_f32_e32 v51, v40
	s_and_b64 vcc, exec, s[0:1]
	v_add_f32_e32 v40, 1.0, v41
	v_rcp_f32_e32 v41, v40
	v_mul_f32_e32 v49, v49, v51
	v_mul_f32_e32 v51, v48, v49
	v_mov_b32_e32 v48, v42
	v_mov_b32_e32 v49, v46
	v_pk_mul_f32 v[48:49], v[48:49], v[72:73] op_sel_hi:[1,0]
	v_mov_b32_e32 v46, v43
	v_mul_f32_e32 v42, 0xbfb8aa3b, v49
	v_mul_f32_e32 v41, v45, v41
	v_exp_f32_e32 v45, v42
	v_pk_mul_f32 v[42:43], v[46:47], v[72:73] op_sel_hi:[1,0]
	v_mul_f32_e32 v41, v44, v41
	v_mul_f32_e32 v46, 0xbfb8aa3b, v43
	v_exp_f32_e32 v46, v46
	v_add_f32_e32 v44, 1.0, v45
	v_rcp_f32_e32 v47, v44
	v_mov_b32_e32 v45, v36
	v_add_f32_e32 v44, 1.0, v46
	v_rcp_f32_e32 v46, v44
	v_mov_b32_e32 v44, v32
	v_pk_mul_f32 v[44:45], v[44:45], v[72:73] op_sel_hi:[1,0]
	v_mul_f32_e32 v36, v49, v47
	v_mul_f32_e32 v32, 0xbfb8aa3b, v45
	v_exp_f32_e32 v32, v32
	v_mul_f32_e32 v47, v48, v36
	v_mov_b32_e32 v36, v33
	v_mul_f32_e32 v43, v43, v46
	v_add_f32_e32 v32, 1.0, v32
	v_rcp_f32_e32 v46, v32
	v_pk_mul_f32 v[32:33], v[36:37], v[72:73] op_sel_hi:[1,0]
	v_mul_f32_e32 v42, v42, v43
	v_mul_f32_e32 v36, 0xbfb8aa3b, v33
	v_exp_f32_e32 v36, v36
	v_mul_f32_e32 v37, v45, v46
	v_mul_f32_e32 v43, v44, v37
	v_mov_b32_e32 v37, v38
	v_add_f32_e32 v36, 1.0, v36
	v_rcp_f32_e32 v44, v36
	v_mov_b32_e32 v36, v34
	v_pk_mul_f32 v[36:37], v[36:37], v[72:73] op_sel_hi:[1,0]
	v_mov_b32_e32 v38, v35
	v_mul_f32_e32 v34, 0xbfb8aa3b, v37
	v_exp_f32_e32 v45, v34
	v_pk_mul_f32 v[34:35], v[38:39], v[72:73] op_sel_hi:[1,0]
	v_mul_f32_e32 v33, v33, v44
	v_mul_f32_e32 v38, 0xbfb8aa3b, v35
	v_exp_f32_e32 v38, v38
	v_add_f32_e32 v39, 1.0, v45
	v_rcp_f32_e32 v39, v39
	v_mul_f32_e32 v44, v32, v33
	v_add_f32_e32 v38, 1.0, v38
	v_rcp_f32_e32 v38, v38
	v_mul_f32_e32 v32, v37, v39
	v_mul_f32_e32 v36, v36, v32
	v_mov_b32_e32 v40, 1.0
	v_mul_f32_e32 v32, v35, v38
	v_mul_f32_e32 v35, v34, v32
	v_cvt_pk_bf16_f32 v32, v51, v41
	v_cvt_pk_bf16_f32 v33, v47, v42
	v_cvt_pk_bf16_f32 v34, v43, v44
	v_cvt_pk_bf16_f32 v35, v36, v35
	v_mov_b64_e32 v[36:37], s[30:31]
	v_mad_i64_i32 v[36:37], s[8:9], v50, s60, v[36:37]
	v_lshl_add_u64 v[36:37], v[120:121], 1, v[36:37]
	global_store_dwordx4 v[36:37], v[32:35], off
	s_nop 1
	v_mov_b32_e32 v32, 1.0
	s_cbranch_vccnz .LBB0_1174
	s_waitcnt vmcnt(7)
	v_pk_add_f32 v[34:35], v[176:177], v[180:181]
	v_pk_add_f32 v[32:33], v[174:175], v[178:179]
	v_pk_add_f32 v[36:37], v[184:185], v[188:189]
	v_pk_add_f32 v[38:39], v[182:183], v[186:187]
	v_pk_add_f32 v[34:35], v[34:35], v[36:37]
	v_pk_add_f32 v[32:33], v[32:33], v[38:39]
	s_nop 0
	v_pk_mov_b32 v[36:37], v[32:33], v[34:35] op_sel:[1,0]
	v_mov_b32_e32 v33, v35
	v_pk_add_f32 v[32:33], v[36:37], v[32:33]
	s_nop 0
	v_add_f32_e32 v32, v32, v33
	v_fmamk_f32 v32, v32, 0x3a800000, v156
	v_rsq_f32_e32 v252, v32
	s_nop 0
	v_mul_f32_e32 v250, v32, v252
	v_fma_f32 v250, -v250, v252, 1.0
	v_mul_f32_e32 v251, 0.5, v252
	v_fma_f32 v32, v251, v250, v252
.LBB0_1174:
	v_mov_b32_e32 v34, v24
	v_mov_b32_e32 v35, v28
	v_pk_mul_f32 v[34:35], v[34:35], v[32:33] op_sel_hi:[1,0]
	v_mov_b32_e32 v28, v25
	v_mul_f32_e32 v24, 0xbfb8aa3b, v35
	v_exp_f32_e32 v33, v24
	s_and_b64 vcc, exec, s[0:1]
	v_pk_mul_f32 v[24:25], v[28:29], v[32:33] op_sel_hi:[1,0]
	s_nop 0
	v_mul_f32_e32 v28, 0xbfb8aa3b, v25
	v_exp_f32_e32 v28, v28
	v_add_f32_e32 v29, 1.0, v33
	v_rcp_f32_e32 v29, v29
	v_add_u32_e32 v33, 0xa0, v144
	v_add_f32_e32 v28, 1.0, v28
	v_rcp_f32_e32 v28, v28
	v_mul_f32_e32 v29, v35, v29
	v_mul_f32_e32 v34, v34, v29
	v_mov_b32_e32 v29, v30
	v_mul_f32_e32 v25, v25, v28
	v_mov_b32_e32 v28, v26
	v_pk_mul_f32 v[28:29], v[28:29], v[32:33] op_sel_hi:[1,0]
	v_mov_b32_e32 v30, v27
	v_mul_f32_e32 v26, 0xbfb8aa3b, v29
	v_exp_f32_e32 v35, v26
	v_pk_mul_f32 v[26:27], v[30:31], v[32:33] op_sel_hi:[1,0]
	v_mul_f32_e32 v31, v24, v25
	v_mul_f32_e32 v30, 0xbfb8aa3b, v27
	v_exp_f32_e32 v30, v30
	v_add_f32_e32 v24, 1.0, v35
	v_rcp_f32_e32 v35, v24
	v_mov_b32_e32 v25, v20
	v_add_f32_e32 v24, 1.0, v30
	v_rcp_f32_e32 v30, v24
	v_mov_b32_e32 v24, v16
	v_pk_mul_f32 v[24:25], v[24:25], v[32:33] op_sel_hi:[1,0]
	v_mul_f32_e32 v20, v29, v35
	v_mul_f32_e32 v16, 0xbfb8aa3b, v25
	v_exp_f32_e32 v16, v16
	v_mul_f32_e32 v28, v28, v20
	v_mov_b32_e32 v20, v17
	v_mul_f32_e32 v27, v27, v30
	v_add_f32_e32 v16, 1.0, v16
	v_rcp_f32_e32 v29, v16
	v_pk_mul_f32 v[16:17], v[20:21], v[32:33] op_sel_hi:[1,0]
	v_mul_f32_e32 v26, v26, v27
	v_mul_f32_e32 v20, 0xbfb8aa3b, v17
	v_exp_f32_e32 v20, v20
	v_mul_f32_e32 v21, v25, v29
	v_mul_f32_e32 v24, v24, v21
	v_mov_b32_e32 v21, v22
	v_add_f32_e32 v20, 1.0, v20
	v_rcp_f32_e32 v25, v20
	v_mov_b32_e32 v20, v18
	v_pk_mul_f32 v[20:21], v[20:21], v[32:33] op_sel_hi:[1,0]
	v_mov_b32_e32 v22, v19
	v_mul_f32_e32 v18, 0xbfb8aa3b, v21
	v_exp_f32_e32 v27, v18
	v_pk_mul_f32 v[18:19], v[22:23], v[32:33] op_sel_hi:[1,0]
	v_mul_f32_e32 v17, v17, v25
	v_mul_f32_e32 v22, 0xbfb8aa3b, v19
	v_exp_f32_e32 v22, v22
	v_add_f32_e32 v23, 1.0, v27
	v_rcp_f32_e32 v23, v23
	v_mul_f32_e32 v25, v16, v17
	v_add_f32_e32 v22, 1.0, v22
	v_rcp_f32_e32 v22, v22
	v_mul_f32_e32 v16, v21, v23
	v_mul_f32_e32 v20, v20, v16
	v_mul_f32_e32 v16, v19, v22
	v_mul_f32_e32 v19, v18, v16
	v_cvt_pk_bf16_f32 v16, v34, v31
	v_cvt_pk_bf16_f32 v17, v28, v26
	v_cvt_pk_bf16_f32 v18, v24, v25
	v_cvt_pk_bf16_f32 v19, v20, v19
	v_mov_b64_e32 v[20:21], s[30:31]
	v_mad_i64_i32 v[20:21], s[8:9], v33, s60, v[20:21]
	v_lshl_add_u64 v[20:21], v[120:121], 1, v[20:21]
	global_store_dwordx4 v[20:21], v[16:19], off
	s_cbranch_vccnz .LBB0_1176
	s_waitcnt vmcnt(3)
	v_pk_add_f32 v[18:19], v[192:193], v[196:197]
	v_pk_add_f32 v[16:17], v[190:191], v[194:195]
	v_pk_add_f32 v[20:21], v[200:201], v[204:205]
	v_pk_add_f32 v[22:23], v[198:199], v[202:203]
	v_pk_add_f32 v[18:19], v[18:19], v[20:21]
	v_pk_add_f32 v[16:17], v[16:17], v[22:23]
	s_nop 0
	v_pk_mov_b32 v[20:21], v[16:17], v[18:19] op_sel:[1,0]
	v_mov_b32_e32 v17, v19
	v_pk_add_f32 v[16:17], v[20:21], v[16:17]
	s_nop 0
	v_add_f32_e32 v16, v16, v17
	v_fmamk_f32 v16, v16, 0x3a800000, v156
	v_rsq_f32_e32 v252, v16
	s_nop 0
	v_mul_f32_e32 v250, v16, v252
	v_fma_f32 v250, -v250, v252, 1.0
	v_mul_f32_e32 v251, 0.5, v252
	v_fma_f32 v40, v251, v250, v252
